# conv module rows rewritten by hand: 38 input rows loaded up front, taps in registers, LayerNorm reductions batched over the 8 tokens
# speedup vs baseline: 1.0124x; 1.0089x over previous
.LBB0_299:
	s_or_b64 exec, exec, s[0:1]
	v_mov_b32_e32 v0, 0x20488
	s_waitcnt vmcnt(0) lgkmcnt(0)
	s_barrier
	v_readlane_b32 s4, v255, 16
	v_add_u32_e32 v0, 0, v0
	ds_read2_b32 v[0:1], v0 offset1:1
	v_readlane_b32 s5, v255, 17
	s_lshl_b32 s4, s4, 8
	s_ashr_i32 s5, s4, 31
	v_lshlrev_b32_e32 v96, 2, v246
	s_waitcnt lgkmcnt(0)
	v_readfirstlane_b32 s0, v0
	v_mov_b32_e32 v0, 0x20490
	v_readfirstlane_b32 s1, v1
	v_add_u32_e32 v0, 0, v0
	ds_read2_b32 v[0:1], v0 offset1:1
	s_cmpk_gt_i32 s46, 0xfff
	v_lshlrev_b32_e32 v106, 1, v96
	s_waitcnt lgkmcnt(0)
	v_readfirstlane_b32 s2, v0
	v_mov_b32_e32 v0, 0x20498
	v_readfirstlane_b32 s6, v1
	v_add_u32_e32 v0, 0, v0
	ds_read2_b32 v[0:1], v0 offset1:1
	s_waitcnt lgkmcnt(0)
	v_readfirstlane_b32 s7, v0
	v_readfirstlane_b32 s8, v1
	s_cbranch_scc1 .LBB0_362
	s_lshl_b64 s[14:15], s[4:5], 2
	s_add_u32 s18, s2, s14
	s_addc_u32 s19, s6, s15
	s_add_u32 s6, s7, s14
	s_addc_u32 s7, s8, s15
	s_add_u32 s0, s0, s14
	s_addc_u32 s1, s1, s15
	v_lshlrev_b32_e32 v105, 4, v246
	v_lshlrev_b32_e32 v104, 3, v246
	global_load_dwordx4 v[84:87], v105, s[0:1]
	global_load_dwordx4 v[88:91], v105, s[18:19]
	global_load_dwordx4 v[92:95], v105, s[6:7]
	v_xor_b32_e32 v98, 1, v246
	v_lshlrev_b32_e32 v98, 2, v98
	v_xor_b32_e32 v99, 2, v246
	v_lshlrev_b32_e32 v99, 2, v99
	v_xor_b32_e32 v100, 4, v246
	v_lshlrev_b32_e32 v100, 2, v100
	v_xor_b32_e32 v101, 8, v246
	v_lshlrev_b32_e32 v101, 2, v101
	v_xor_b32_e32 v102, 16, v246
	v_lshlrev_b32_e32 v102, 2, v102
	v_xor_b32_e32 v103, 32, v246
	v_lshlrev_b32_e32 v103, 2, v103
	s_mov_b32 s16, s46
.Lcv_item:
	s_lshl_b32 s18, s16, 3
	s_and_b32 s19, s18, 0xfff
	s_sub_i32 s19, s19, 30
	s_sub_i32 s6, s18, 30
	s_ashr_i32 s15, s6, 31
	s_mov_b32 s14, s6
	s_lshl_b64 s[14:15], s[14:15], 9
	s_add_u32 s72, s70, s14
	s_addc_u32 s73, s71, s15
	s_add_u32 s74, s72, 0x1000
	s_addc_u32 s75, s73, 0
	s_add_u32 s76, s74, 0x1000
	s_addc_u32 s77, s75, 0
	s_add_u32 s78, s76, 0x1000
	s_addc_u32 s79, s77, 0
	s_add_u32 s80, s78, 0x1000
	s_addc_u32 s81, s79, 0
	s_lshl_b32 s14, s18, 11
	s_add_u32 s82, s54, s14
	s_addc_u32 s83, s55, 0
	s_add_u32 s82, s82, 0x600
	s_addc_u32 s83, s83, 0
	s_cmp_ge_i32 s19, 0
	s_cbranch_scc0 .Lcv_slow
	global_load_dwordx2 v[128:129], v104, s[72:73]
	global_load_dwordx2 v[130:131], v104, s[72:73] offset:512
	global_load_dwordx2 v[132:133], v104, s[72:73] offset:1024
	global_load_dwordx2 v[134:135], v104, s[72:73] offset:1536
	global_load_dwordx2 v[136:137], v104, s[72:73] offset:2048
	global_load_dwordx2 v[138:139], v104, s[72:73] offset:2560
	global_load_dwordx2 v[140:141], v104, s[72:73] offset:3072
	global_load_dwordx2 v[142:143], v104, s[72:73] offset:3584
	global_load_dwordx2 v[144:145], v104, s[74:75]
	global_load_dwordx2 v[146:147], v104, s[74:75] offset:512
	global_load_dwordx2 v[148:149], v104, s[74:75] offset:1024
	global_load_dwordx2 v[150:151], v104, s[74:75] offset:1536
	global_load_dwordx2 v[152:153], v104, s[74:75] offset:2048
	global_load_dwordx2 v[154:155], v104, s[74:75] offset:2560
	global_load_dwordx2 v[156:157], v104, s[74:75] offset:3072
	global_load_dwordx2 v[158:159], v104, s[74:75] offset:3584
	global_load_dwordx2 v[160:161], v104, s[76:77]
	global_load_dwordx2 v[162:163], v104, s[76:77] offset:512
	global_load_dwordx2 v[164:165], v104, s[76:77] offset:1024
	global_load_dwordx2 v[166:167], v104, s[76:77] offset:1536
	global_load_dwordx2 v[168:169], v104, s[76:77] offset:2048
	global_load_dwordx2 v[170:171], v104, s[76:77] offset:2560
	global_load_dwordx2 v[172:173], v104, s[76:77] offset:3072
	global_load_dwordx2 v[174:175], v104, s[76:77] offset:3584
	global_load_dwordx2 v[176:177], v104, s[78:79]
	global_load_dwordx2 v[178:179], v104, s[78:79] offset:512
	global_load_dwordx2 v[180:181], v104, s[78:79] offset:1024
	global_load_dwordx2 v[182:183], v104, s[78:79] offset:1536
	global_load_dwordx2 v[184:185], v104, s[78:79] offset:2048
	global_load_dwordx2 v[186:187], v104, s[78:79] offset:2560
	global_load_dwordx2 v[188:189], v104, s[78:79] offset:3072
	global_load_dwordx2 v[190:191], v104, s[78:79] offset:3584
	global_load_dwordx2 v[192:193], v104, s[80:81]
	global_load_dwordx2 v[194:195], v104, s[80:81] offset:512
	global_load_dwordx2 v[196:197], v104, s[80:81] offset:1024
	global_load_dwordx2 v[200:201], v104, s[80:81] offset:1536
	global_load_dwordx2 v[202:203], v104, s[80:81] offset:2048
	global_load_dwordx2 v[204:205], v104, s[80:81] offset:2560
	s_branch .Lcv_loaded
.Lcv_slow:
	s_add_i32 s6, s19, 0
	s_cmp_ge_i32 s6, 0
	s_cbranch_scc0 .Lcv_z0
	global_load_dwordx2 v[128:129], v104, s[72:73]
	s_branch .Lcv_n0
.Lcv_z0:
	v_mov_b32_e32 v128, 0
	v_mov_b32_e32 v129, 0
.Lcv_n0:
	s_add_i32 s6, s19, 1
	s_cmp_ge_i32 s6, 0
	s_cbranch_scc0 .Lcv_z1
	global_load_dwordx2 v[130:131], v104, s[72:73] offset:512
	s_branch .Lcv_n1
.Lcv_z1:
	v_mov_b32_e32 v130, 0
	v_mov_b32_e32 v131, 0
.Lcv_n1:
	s_add_i32 s6, s19, 2
	s_cmp_ge_i32 s6, 0
	s_cbranch_scc0 .Lcv_z2
	global_load_dwordx2 v[132:133], v104, s[72:73] offset:1024
	s_branch .Lcv_n2
.Lcv_z2:
	v_mov_b32_e32 v132, 0
	v_mov_b32_e32 v133, 0
.Lcv_n2:
	s_add_i32 s6, s19, 3
	s_cmp_ge_i32 s6, 0
	s_cbranch_scc0 .Lcv_z3
	global_load_dwordx2 v[134:135], v104, s[72:73] offset:1536
	s_branch .Lcv_n3
.Lcv_z3:
	v_mov_b32_e32 v134, 0
	v_mov_b32_e32 v135, 0
.Lcv_n3:
	s_add_i32 s6, s19, 4
	s_cmp_ge_i32 s6, 0
	s_cbranch_scc0 .Lcv_z4
	global_load_dwordx2 v[136:137], v104, s[72:73] offset:2048
	s_branch .Lcv_n4
.Lcv_z4:
	v_mov_b32_e32 v136, 0
	v_mov_b32_e32 v137, 0
.Lcv_n4:
	s_add_i32 s6, s19, 5
	s_cmp_ge_i32 s6, 0
	s_cbranch_scc0 .Lcv_z5
	global_load_dwordx2 v[138:139], v104, s[72:73] offset:2560
	s_branch .Lcv_n5
.Lcv_z5:
	v_mov_b32_e32 v138, 0
	v_mov_b32_e32 v139, 0
.Lcv_n5:
	s_add_i32 s6, s19, 6
	s_cmp_ge_i32 s6, 0
	s_cbranch_scc0 .Lcv_z6
	global_load_dwordx2 v[140:141], v104, s[72:73] offset:3072
	s_branch .Lcv_n6
.Lcv_z6:
	v_mov_b32_e32 v140, 0
	v_mov_b32_e32 v141, 0
.Lcv_n6:
	s_add_i32 s6, s19, 7
	s_cmp_ge_i32 s6, 0
	s_cbranch_scc0 .Lcv_z7
	global_load_dwordx2 v[142:143], v104, s[72:73] offset:3584
	s_branch .Lcv_n7
.Lcv_z7:
	v_mov_b32_e32 v142, 0
	v_mov_b32_e32 v143, 0
.Lcv_n7:
	s_add_i32 s6, s19, 8
	s_cmp_ge_i32 s6, 0
	s_cbranch_scc0 .Lcv_z8
	global_load_dwordx2 v[144:145], v104, s[74:75]
	s_branch .Lcv_n8
.Lcv_z8:
	v_mov_b32_e32 v144, 0
	v_mov_b32_e32 v145, 0
.Lcv_n8:
	s_add_i32 s6, s19, 9
	s_cmp_ge_i32 s6, 0
	s_cbranch_scc0 .Lcv_z9
	global_load_dwordx2 v[146:147], v104, s[74:75] offset:512
	s_branch .Lcv_n9
.Lcv_z9:
	v_mov_b32_e32 v146, 0
	v_mov_b32_e32 v147, 0
.Lcv_n9:
	s_add_i32 s6, s19, 10
	s_cmp_ge_i32 s6, 0
	s_cbranch_scc0 .Lcv_z10
	global_load_dwordx2 v[148:149], v104, s[74:75] offset:1024
	s_branch .Lcv_n10
.Lcv_z10:
	v_mov_b32_e32 v148, 0
	v_mov_b32_e32 v149, 0
.Lcv_n10:
	s_add_i32 s6, s19, 11
	s_cmp_ge_i32 s6, 0
	s_cbranch_scc0 .Lcv_z11
	global_load_dwordx2 v[150:151], v104, s[74:75] offset:1536
	s_branch .Lcv_n11
.Lcv_z11:
	v_mov_b32_e32 v150, 0
	v_mov_b32_e32 v151, 0
.Lcv_n11:
	s_add_i32 s6, s19, 12
	s_cmp_ge_i32 s6, 0
	s_cbranch_scc0 .Lcv_z12
	global_load_dwordx2 v[152:153], v104, s[74:75] offset:2048
	s_branch .Lcv_n12
.Lcv_z12:
	v_mov_b32_e32 v152, 0
	v_mov_b32_e32 v153, 0
.Lcv_n12:
	s_add_i32 s6, s19, 13
	s_cmp_ge_i32 s6, 0
	s_cbranch_scc0 .Lcv_z13
	global_load_dwordx2 v[154:155], v104, s[74:75] offset:2560
	s_branch .Lcv_n13
.Lcv_z13:
	v_mov_b32_e32 v154, 0
	v_mov_b32_e32 v155, 0
.Lcv_n13:
	s_add_i32 s6, s19, 14
	s_cmp_ge_i32 s6, 0
	s_cbranch_scc0 .Lcv_z14
	global_load_dwordx2 v[156:157], v104, s[74:75] offset:3072
	s_branch .Lcv_n14
.Lcv_z14:
	v_mov_b32_e32 v156, 0
	v_mov_b32_e32 v157, 0
.Lcv_n14:
	s_add_i32 s6, s19, 15
	s_cmp_ge_i32 s6, 0
	s_cbranch_scc0 .Lcv_z15
	global_load_dwordx2 v[158:159], v104, s[74:75] offset:3584
	s_branch .Lcv_n15
.Lcv_z15:
	v_mov_b32_e32 v158, 0
	v_mov_b32_e32 v159, 0
.Lcv_n15:
	s_add_i32 s6, s19, 16
	s_cmp_ge_i32 s6, 0
	s_cbranch_scc0 .Lcv_z16
	global_load_dwordx2 v[160:161], v104, s[76:77]
	s_branch .Lcv_n16
.Lcv_z16:
	v_mov_b32_e32 v160, 0
	v_mov_b32_e32 v161, 0
.Lcv_n16:
	s_add_i32 s6, s19, 17
	s_cmp_ge_i32 s6, 0
	s_cbranch_scc0 .Lcv_z17
	global_load_dwordx2 v[162:163], v104, s[76:77] offset:512
	s_branch .Lcv_n17
.Lcv_z17:
	v_mov_b32_e32 v162, 0
	v_mov_b32_e32 v163, 0
.Lcv_n17:
	s_add_i32 s6, s19, 18
	s_cmp_ge_i32 s6, 0
	s_cbranch_scc0 .Lcv_z18
	global_load_dwordx2 v[164:165], v104, s[76:77] offset:1024
	s_branch .Lcv_n18
.Lcv_z18:
	v_mov_b32_e32 v164, 0
	v_mov_b32_e32 v165, 0
.Lcv_n18:
	s_add_i32 s6, s19, 19
	s_cmp_ge_i32 s6, 0
	s_cbranch_scc0 .Lcv_z19
	global_load_dwordx2 v[166:167], v104, s[76:77] offset:1536
	s_branch .Lcv_n19
.Lcv_z19:
	v_mov_b32_e32 v166, 0
	v_mov_b32_e32 v167, 0
.Lcv_n19:
	s_add_i32 s6, s19, 20
	s_cmp_ge_i32 s6, 0
	s_cbranch_scc0 .Lcv_z20
	global_load_dwordx2 v[168:169], v104, s[76:77] offset:2048
	s_branch .Lcv_n20
.Lcv_z20:
	v_mov_b32_e32 v168, 0
	v_mov_b32_e32 v169, 0
.Lcv_n20:
	s_add_i32 s6, s19, 21
	s_cmp_ge_i32 s6, 0
	s_cbranch_scc0 .Lcv_z21
	global_load_dwordx2 v[170:171], v104, s[76:77] offset:2560
	s_branch .Lcv_n21
.Lcv_z21:
	v_mov_b32_e32 v170, 0
	v_mov_b32_e32 v171, 0
.Lcv_n21:
	s_add_i32 s6, s19, 22
	s_cmp_ge_i32 s6, 0
	s_cbranch_scc0 .Lcv_z22
	global_load_dwordx2 v[172:173], v104, s[76:77] offset:3072
	s_branch .Lcv_n22
.Lcv_z22:
	v_mov_b32_e32 v172, 0
	v_mov_b32_e32 v173, 0
.Lcv_n22:
	s_add_i32 s6, s19, 23
	s_cmp_ge_i32 s6, 0
	s_cbranch_scc0 .Lcv_z23
	global_load_dwordx2 v[174:175], v104, s[76:77] offset:3584
	s_branch .Lcv_n23
.Lcv_z23:
	v_mov_b32_e32 v174, 0
	v_mov_b32_e32 v175, 0
.Lcv_n23:
	s_add_i32 s6, s19, 24
	s_cmp_ge_i32 s6, 0
	s_cbranch_scc0 .Lcv_z24
	global_load_dwordx2 v[176:177], v104, s[78:79]
	s_branch .Lcv_n24
.Lcv_z24:
	v_mov_b32_e32 v176, 0
	v_mov_b32_e32 v177, 0
.Lcv_n24:
	s_add_i32 s6, s19, 25
	s_cmp_ge_i32 s6, 0
	s_cbranch_scc0 .Lcv_z25
	global_load_dwordx2 v[178:179], v104, s[78:79] offset:512
	s_branch .Lcv_n25
.Lcv_z25:
	v_mov_b32_e32 v178, 0
	v_mov_b32_e32 v179, 0
.Lcv_n25:
	s_add_i32 s6, s19, 26
	s_cmp_ge_i32 s6, 0
	s_cbranch_scc0 .Lcv_z26
	global_load_dwordx2 v[180:181], v104, s[78:79] offset:1024
	s_branch .Lcv_n26
.Lcv_z26:
	v_mov_b32_e32 v180, 0
	v_mov_b32_e32 v181, 0
.Lcv_n26:
	s_add_i32 s6, s19, 27
	s_cmp_ge_i32 s6, 0
	s_cbranch_scc0 .Lcv_z27
	global_load_dwordx2 v[182:183], v104, s[78:79] offset:1536
	s_branch .Lcv_n27
.Lcv_z27:
	v_mov_b32_e32 v182, 0
	v_mov_b32_e32 v183, 0
.Lcv_n27:
	s_add_i32 s6, s19, 28
	s_cmp_ge_i32 s6, 0
	s_cbranch_scc0 .Lcv_z28
	global_load_dwordx2 v[184:185], v104, s[78:79] offset:2048
	s_branch .Lcv_n28
.Lcv_z28:
	v_mov_b32_e32 v184, 0
	v_mov_b32_e32 v185, 0
.Lcv_n28:
	s_add_i32 s6, s19, 29
	s_cmp_ge_i32 s6, 0
	s_cbranch_scc0 .Lcv_z29
	global_load_dwordx2 v[186:187], v104, s[78:79] offset:2560
	s_branch .Lcv_n29
.Lcv_z29:
	v_mov_b32_e32 v186, 0
	v_mov_b32_e32 v187, 0
.Lcv_n29:
	global_load_dwordx2 v[188:189], v104, s[78:79] offset:3072
	global_load_dwordx2 v[190:191], v104, s[78:79] offset:3584
	global_load_dwordx2 v[192:193], v104, s[80:81]
	global_load_dwordx2 v[194:195], v104, s[80:81] offset:512
	global_load_dwordx2 v[196:197], v104, s[80:81] offset:1024
	global_load_dwordx2 v[200:201], v104, s[80:81] offset:1536
	global_load_dwordx2 v[202:203], v104, s[80:81] offset:2048
	global_load_dwordx2 v[204:205], v104, s[80:81] offset:2560
.Lcv_loaded:
	ds_read_b128 v[32:35], v105 offset:0
	ds_read_b128 v[36:39], v105 offset:1024
	ds_read_b128 v[40:43], v105 offset:2048
	ds_read_b128 v[44:47], v105 offset:3072
	ds_read_b128 v[48:51], v105 offset:4096
	ds_read_b128 v[52:55], v105 offset:5120
	ds_read_b128 v[56:59], v105 offset:6144
	ds_read_b128 v[60:63], v105 offset:7168
	ds_read_b128 v[64:67], v105 offset:8192
	ds_read_b128 v[68:71], v105 offset:9216
	ds_read_b128 v[72:75], v105 offset:10240
	ds_read_b128 v[208:211], v105 offset:11264
	ds_read_b128 v[212:215], v105 offset:12288
	ds_read_b128 v[216:219], v105 offset:13312
	ds_read_b128 v[220:223], v105 offset:14336
	ds_read_b128 v[224:227], v105 offset:15360
	ds_read_b128 v[228:231], v105 offset:16384
	ds_read_b128 v[232:235], v105 offset:17408
	ds_read_b128 v[236:239], v105 offset:18432
	s_waitcnt vmcnt(0)
	v_mov_b32_e32 v0, v84
	v_mov_b32_e32 v1, v85
	v_mov_b32_e32 v2, v86
	v_mov_b32_e32 v3, v87
	v_mov_b32_e32 v4, v84
	v_mov_b32_e32 v5, v85
	v_mov_b32_e32 v6, v86
	v_mov_b32_e32 v7, v87
	v_mov_b32_e32 v8, v84
	v_mov_b32_e32 v9, v85
	v_mov_b32_e32 v10, v86
	v_mov_b32_e32 v11, v87
	v_mov_b32_e32 v12, v84
	v_mov_b32_e32 v13, v85
	v_mov_b32_e32 v14, v86
	v_mov_b32_e32 v15, v87
	v_mov_b32_e32 v16, v84
	v_mov_b32_e32 v17, v85
	v_mov_b32_e32 v18, v86
	v_mov_b32_e32 v19, v87
	v_mov_b32_e32 v20, v84
	v_mov_b32_e32 v21, v85
	v_mov_b32_e32 v22, v86
	v_mov_b32_e32 v23, v87
	v_mov_b32_e32 v24, v84
	v_mov_b32_e32 v25, v85
	v_mov_b32_e32 v26, v86
	v_mov_b32_e32 v27, v87
	v_mov_b32_e32 v28, v84
	v_mov_b32_e32 v29, v85
	v_mov_b32_e32 v30, v86
	v_mov_b32_e32 v31, v87
	s_waitcnt lgkmcnt(0)
	v_lshlrev_b32_e32 v76, 16, v128
	v_and_b32_e32 v77, 0xffff0000, v128
	v_lshlrev_b32_e32 v78, 16, v129
	v_and_b32_e32 v79, 0xffff0000, v129
	v_lshlrev_b32_e32 v80, 16, v130
	v_and_b32_e32 v81, 0xffff0000, v130
	v_lshlrev_b32_e32 v82, 16, v131
	v_and_b32_e32 v83, 0xffff0000, v131
	v_pk_fma_f32 v[0:1], v[32:33], v[76:77], v[0:1]
	v_pk_fma_f32 v[2:3], v[34:35], v[78:79], v[2:3]
	v_lshlrev_b32_e32 v76, 16, v132
	v_and_b32_e32 v77, 0xffff0000, v132
	v_lshlrev_b32_e32 v78, 16, v133
	v_and_b32_e32 v79, 0xffff0000, v133
	v_pk_fma_f32 v[0:1], v[36:37], v[80:81], v[0:1]
	v_pk_fma_f32 v[2:3], v[38:39], v[82:83], v[2:3]
	v_pk_fma_f32 v[4:5], v[32:33], v[80:81], v[4:5]
	v_pk_fma_f32 v[6:7], v[34:35], v[82:83], v[6:7]
	v_lshlrev_b32_e32 v80, 16, v134
	v_and_b32_e32 v81, 0xffff0000, v134
	v_lshlrev_b32_e32 v82, 16, v135
	v_and_b32_e32 v83, 0xffff0000, v135
	v_pk_fma_f32 v[0:1], v[40:41], v[76:77], v[0:1]
	v_pk_fma_f32 v[2:3], v[42:43], v[78:79], v[2:3]
	v_pk_fma_f32 v[4:5], v[36:37], v[76:77], v[4:5]
	v_pk_fma_f32 v[6:7], v[38:39], v[78:79], v[6:7]
	v_pk_fma_f32 v[8:9], v[32:33], v[76:77], v[8:9]
	v_pk_fma_f32 v[10:11], v[34:35], v[78:79], v[10:11]
	v_lshlrev_b32_e32 v76, 16, v136
	v_and_b32_e32 v77, 0xffff0000, v136
	v_lshlrev_b32_e32 v78, 16, v137
	v_and_b32_e32 v79, 0xffff0000, v137
	v_pk_fma_f32 v[0:1], v[44:45], v[80:81], v[0:1]
	v_pk_fma_f32 v[2:3], v[46:47], v[82:83], v[2:3]
	v_pk_fma_f32 v[4:5], v[40:41], v[80:81], v[4:5]
	v_pk_fma_f32 v[6:7], v[42:43], v[82:83], v[6:7]
	v_pk_fma_f32 v[8:9], v[36:37], v[80:81], v[8:9]
	v_pk_fma_f32 v[10:11], v[38:39], v[82:83], v[10:11]
	v_pk_fma_f32 v[12:13], v[32:33], v[80:81], v[12:13]
	v_pk_fma_f32 v[14:15], v[34:35], v[82:83], v[14:15]
	v_lshlrev_b32_e32 v80, 16, v138
	v_and_b32_e32 v81, 0xffff0000, v138
	v_lshlrev_b32_e32 v82, 16, v139
	v_and_b32_e32 v83, 0xffff0000, v139
	v_pk_fma_f32 v[0:1], v[48:49], v[76:77], v[0:1]
	v_pk_fma_f32 v[2:3], v[50:51], v[78:79], v[2:3]
	v_pk_fma_f32 v[4:5], v[44:45], v[76:77], v[4:5]
	v_pk_fma_f32 v[6:7], v[46:47], v[78:79], v[6:7]
	v_pk_fma_f32 v[8:9], v[40:41], v[76:77], v[8:9]
	v_pk_fma_f32 v[10:11], v[42:43], v[78:79], v[10:11]
	v_pk_fma_f32 v[12:13], v[36:37], v[76:77], v[12:13]
	v_pk_fma_f32 v[14:15], v[38:39], v[78:79], v[14:15]
	v_pk_fma_f32 v[16:17], v[32:33], v[76:77], v[16:17]
	v_pk_fma_f32 v[18:19], v[34:35], v[78:79], v[18:19]
	v_lshlrev_b32_e32 v76, 16, v140
	v_and_b32_e32 v77, 0xffff0000, v140
	v_lshlrev_b32_e32 v78, 16, v141
	v_and_b32_e32 v79, 0xffff0000, v141
	v_pk_fma_f32 v[0:1], v[52:53], v[80:81], v[0:1]
	v_pk_fma_f32 v[2:3], v[54:55], v[82:83], v[2:3]
	v_pk_fma_f32 v[4:5], v[48:49], v[80:81], v[4:5]
	v_pk_fma_f32 v[6:7], v[50:51], v[82:83], v[6:7]
	v_pk_fma_f32 v[8:9], v[44:45], v[80:81], v[8:9]
	v_pk_fma_f32 v[10:11], v[46:47], v[82:83], v[10:11]
	v_pk_fma_f32 v[12:13], v[40:41], v[80:81], v[12:13]
	v_pk_fma_f32 v[14:15], v[42:43], v[82:83], v[14:15]
	v_pk_fma_f32 v[16:17], v[36:37], v[80:81], v[16:17]
	v_pk_fma_f32 v[18:19], v[38:39], v[82:83], v[18:19]
	v_pk_fma_f32 v[20:21], v[32:33], v[80:81], v[20:21]
	v_pk_fma_f32 v[22:23], v[34:35], v[82:83], v[22:23]
	v_lshlrev_b32_e32 v80, 16, v142
	v_and_b32_e32 v81, 0xffff0000, v142
	v_lshlrev_b32_e32 v82, 16, v143
	v_and_b32_e32 v83, 0xffff0000, v143
	v_pk_fma_f32 v[0:1], v[56:57], v[76:77], v[0:1]
	v_pk_fma_f32 v[2:3], v[58:59], v[78:79], v[2:3]
	v_pk_fma_f32 v[4:5], v[52:53], v[76:77], v[4:5]
	v_pk_fma_f32 v[6:7], v[54:55], v[78:79], v[6:7]
	v_pk_fma_f32 v[8:9], v[48:49], v[76:77], v[8:9]
	v_pk_fma_f32 v[10:11], v[50:51], v[78:79], v[10:11]
	v_pk_fma_f32 v[12:13], v[44:45], v[76:77], v[12:13]
	v_pk_fma_f32 v[14:15], v[46:47], v[78:79], v[14:15]
	v_pk_fma_f32 v[16:17], v[40:41], v[76:77], v[16:17]
	v_pk_fma_f32 v[18:19], v[42:43], v[78:79], v[18:19]
	v_pk_fma_f32 v[20:21], v[36:37], v[76:77], v[20:21]
	v_pk_fma_f32 v[22:23], v[38:39], v[78:79], v[22:23]
	v_pk_fma_f32 v[24:25], v[32:33], v[76:77], v[24:25]
	v_pk_fma_f32 v[26:27], v[34:35], v[78:79], v[26:27]
	v_lshlrev_b32_e32 v76, 16, v144
	v_and_b32_e32 v77, 0xffff0000, v144
	v_lshlrev_b32_e32 v78, 16, v145
	v_and_b32_e32 v79, 0xffff0000, v145
	v_pk_fma_f32 v[0:1], v[60:61], v[80:81], v[0:1]
	v_pk_fma_f32 v[2:3], v[62:63], v[82:83], v[2:3]
	v_pk_fma_f32 v[4:5], v[56:57], v[80:81], v[4:5]
	v_pk_fma_f32 v[6:7], v[58:59], v[82:83], v[6:7]
	v_pk_fma_f32 v[8:9], v[52:53], v[80:81], v[8:9]
	v_pk_fma_f32 v[10:11], v[54:55], v[82:83], v[10:11]
	v_pk_fma_f32 v[12:13], v[48:49], v[80:81], v[12:13]
	v_pk_fma_f32 v[14:15], v[50:51], v[82:83], v[14:15]
	v_pk_fma_f32 v[16:17], v[44:45], v[80:81], v[16:17]
	v_pk_fma_f32 v[18:19], v[46:47], v[82:83], v[18:19]
	v_pk_fma_f32 v[20:21], v[40:41], v[80:81], v[20:21]
	v_pk_fma_f32 v[22:23], v[42:43], v[82:83], v[22:23]
	v_pk_fma_f32 v[24:25], v[36:37], v[80:81], v[24:25]
	v_pk_fma_f32 v[26:27], v[38:39], v[82:83], v[26:27]
	v_pk_fma_f32 v[28:29], v[32:33], v[80:81], v[28:29]
	v_pk_fma_f32 v[30:31], v[34:35], v[82:83], v[30:31]
	v_lshlrev_b32_e32 v80, 16, v146
	v_and_b32_e32 v81, 0xffff0000, v146
	v_lshlrev_b32_e32 v82, 16, v147
	v_and_b32_e32 v83, 0xffff0000, v147
	v_pk_fma_f32 v[0:1], v[64:65], v[76:77], v[0:1]
	v_pk_fma_f32 v[2:3], v[66:67], v[78:79], v[2:3]
	v_pk_fma_f32 v[4:5], v[60:61], v[76:77], v[4:5]
	v_pk_fma_f32 v[6:7], v[62:63], v[78:79], v[6:7]
	v_pk_fma_f32 v[8:9], v[56:57], v[76:77], v[8:9]
	v_pk_fma_f32 v[10:11], v[58:59], v[78:79], v[10:11]
	v_pk_fma_f32 v[12:13], v[52:53], v[76:77], v[12:13]
	v_pk_fma_f32 v[14:15], v[54:55], v[78:79], v[14:15]
	v_pk_fma_f32 v[16:17], v[48:49], v[76:77], v[16:17]
	v_pk_fma_f32 v[18:19], v[50:51], v[78:79], v[18:19]
	v_pk_fma_f32 v[20:21], v[44:45], v[76:77], v[20:21]
	v_pk_fma_f32 v[22:23], v[46:47], v[78:79], v[22:23]
	v_pk_fma_f32 v[24:25], v[40:41], v[76:77], v[24:25]
	v_pk_fma_f32 v[26:27], v[42:43], v[78:79], v[26:27]
	v_pk_fma_f32 v[28:29], v[36:37], v[76:77], v[28:29]
	v_pk_fma_f32 v[30:31], v[38:39], v[78:79], v[30:31]
	v_lshlrev_b32_e32 v76, 16, v148
	v_and_b32_e32 v77, 0xffff0000, v148
	v_lshlrev_b32_e32 v78, 16, v149
	v_and_b32_e32 v79, 0xffff0000, v149
	v_pk_fma_f32 v[0:1], v[68:69], v[80:81], v[0:1]
	v_pk_fma_f32 v[2:3], v[70:71], v[82:83], v[2:3]
	v_pk_fma_f32 v[4:5], v[64:65], v[80:81], v[4:5]
	v_pk_fma_f32 v[6:7], v[66:67], v[82:83], v[6:7]
	v_pk_fma_f32 v[8:9], v[60:61], v[80:81], v[8:9]
	v_pk_fma_f32 v[10:11], v[62:63], v[82:83], v[10:11]
	v_pk_fma_f32 v[12:13], v[56:57], v[80:81], v[12:13]
	v_pk_fma_f32 v[14:15], v[58:59], v[82:83], v[14:15]
	v_pk_fma_f32 v[16:17], v[52:53], v[80:81], v[16:17]
	v_pk_fma_f32 v[18:19], v[54:55], v[82:83], v[18:19]
	v_pk_fma_f32 v[20:21], v[48:49], v[80:81], v[20:21]
	v_pk_fma_f32 v[22:23], v[50:51], v[82:83], v[22:23]
	v_pk_fma_f32 v[24:25], v[44:45], v[80:81], v[24:25]
	v_pk_fma_f32 v[26:27], v[46:47], v[82:83], v[26:27]
	v_pk_fma_f32 v[28:29], v[40:41], v[80:81], v[28:29]
	v_pk_fma_f32 v[30:31], v[42:43], v[82:83], v[30:31]
	v_lshlrev_b32_e32 v80, 16, v150
	v_and_b32_e32 v81, 0xffff0000, v150
	v_lshlrev_b32_e32 v82, 16, v151
	v_and_b32_e32 v83, 0xffff0000, v151
	v_pk_fma_f32 v[0:1], v[72:73], v[76:77], v[0:1]
	v_pk_fma_f32 v[2:3], v[74:75], v[78:79], v[2:3]
	v_pk_fma_f32 v[4:5], v[68:69], v[76:77], v[4:5]
	v_pk_fma_f32 v[6:7], v[70:71], v[78:79], v[6:7]
	v_pk_fma_f32 v[8:9], v[64:65], v[76:77], v[8:9]
	v_pk_fma_f32 v[10:11], v[66:67], v[78:79], v[10:11]
	v_pk_fma_f32 v[12:13], v[60:61], v[76:77], v[12:13]
	v_pk_fma_f32 v[14:15], v[62:63], v[78:79], v[14:15]
	v_pk_fma_f32 v[16:17], v[56:57], v[76:77], v[16:17]
	v_pk_fma_f32 v[18:19], v[58:59], v[78:79], v[18:19]
	v_pk_fma_f32 v[20:21], v[52:53], v[76:77], v[20:21]
	v_pk_fma_f32 v[22:23], v[54:55], v[78:79], v[22:23]
	v_pk_fma_f32 v[24:25], v[48:49], v[76:77], v[24:25]
	v_pk_fma_f32 v[26:27], v[50:51], v[78:79], v[26:27]
	v_pk_fma_f32 v[28:29], v[44:45], v[76:77], v[28:29]
	v_pk_fma_f32 v[30:31], v[46:47], v[78:79], v[30:31]
	v_lshlrev_b32_e32 v76, 16, v152
	v_and_b32_e32 v77, 0xffff0000, v152
	v_lshlrev_b32_e32 v78, 16, v153
	v_and_b32_e32 v79, 0xffff0000, v153
	v_pk_fma_f32 v[0:1], v[208:209], v[80:81], v[0:1]
	v_pk_fma_f32 v[2:3], v[210:211], v[82:83], v[2:3]
	v_pk_fma_f32 v[4:5], v[72:73], v[80:81], v[4:5]
	v_pk_fma_f32 v[6:7], v[74:75], v[82:83], v[6:7]
	v_pk_fma_f32 v[8:9], v[68:69], v[80:81], v[8:9]
	v_pk_fma_f32 v[10:11], v[70:71], v[82:83], v[10:11]
	v_pk_fma_f32 v[12:13], v[64:65], v[80:81], v[12:13]
	v_pk_fma_f32 v[14:15], v[66:67], v[82:83], v[14:15]
	v_pk_fma_f32 v[16:17], v[60:61], v[80:81], v[16:17]
	v_pk_fma_f32 v[18:19], v[62:63], v[82:83], v[18:19]
	v_pk_fma_f32 v[20:21], v[56:57], v[80:81], v[20:21]
	v_pk_fma_f32 v[22:23], v[58:59], v[82:83], v[22:23]
	v_pk_fma_f32 v[24:25], v[52:53], v[80:81], v[24:25]
	v_pk_fma_f32 v[26:27], v[54:55], v[82:83], v[26:27]
	v_pk_fma_f32 v[28:29], v[48:49], v[80:81], v[28:29]
	v_pk_fma_f32 v[30:31], v[50:51], v[82:83], v[30:31]
	v_lshlrev_b32_e32 v80, 16, v154
	v_and_b32_e32 v81, 0xffff0000, v154
	v_lshlrev_b32_e32 v82, 16, v155
	v_and_b32_e32 v83, 0xffff0000, v155
	v_pk_fma_f32 v[0:1], v[212:213], v[76:77], v[0:1]
	v_pk_fma_f32 v[2:3], v[214:215], v[78:79], v[2:3]
	v_pk_fma_f32 v[4:5], v[208:209], v[76:77], v[4:5]
	v_pk_fma_f32 v[6:7], v[210:211], v[78:79], v[6:7]
	v_pk_fma_f32 v[8:9], v[72:73], v[76:77], v[8:9]
	v_pk_fma_f32 v[10:11], v[74:75], v[78:79], v[10:11]
	v_pk_fma_f32 v[12:13], v[68:69], v[76:77], v[12:13]
	v_pk_fma_f32 v[14:15], v[70:71], v[78:79], v[14:15]
	v_pk_fma_f32 v[16:17], v[64:65], v[76:77], v[16:17]
	v_pk_fma_f32 v[18:19], v[66:67], v[78:79], v[18:19]
	v_pk_fma_f32 v[20:21], v[60:61], v[76:77], v[20:21]
	v_pk_fma_f32 v[22:23], v[62:63], v[78:79], v[22:23]
	v_pk_fma_f32 v[24:25], v[56:57], v[76:77], v[24:25]
	v_pk_fma_f32 v[26:27], v[58:59], v[78:79], v[26:27]
	v_pk_fma_f32 v[28:29], v[52:53], v[76:77], v[28:29]
	v_pk_fma_f32 v[30:31], v[54:55], v[78:79], v[30:31]
	v_lshlrev_b32_e32 v76, 16, v156
	v_and_b32_e32 v77, 0xffff0000, v156
	v_lshlrev_b32_e32 v78, 16, v157
	v_and_b32_e32 v79, 0xffff0000, v157
	v_pk_fma_f32 v[0:1], v[216:217], v[80:81], v[0:1]
	v_pk_fma_f32 v[2:3], v[218:219], v[82:83], v[2:3]
	v_pk_fma_f32 v[4:5], v[212:213], v[80:81], v[4:5]
	v_pk_fma_f32 v[6:7], v[214:215], v[82:83], v[6:7]
	v_pk_fma_f32 v[8:9], v[208:209], v[80:81], v[8:9]
	v_pk_fma_f32 v[10:11], v[210:211], v[82:83], v[10:11]
	v_pk_fma_f32 v[12:13], v[72:73], v[80:81], v[12:13]
	v_pk_fma_f32 v[14:15], v[74:75], v[82:83], v[14:15]
	v_pk_fma_f32 v[16:17], v[68:69], v[80:81], v[16:17]
	v_pk_fma_f32 v[18:19], v[70:71], v[82:83], v[18:19]
	v_pk_fma_f32 v[20:21], v[64:65], v[80:81], v[20:21]
	v_pk_fma_f32 v[22:23], v[66:67], v[82:83], v[22:23]
	v_pk_fma_f32 v[24:25], v[60:61], v[80:81], v[24:25]
	v_pk_fma_f32 v[26:27], v[62:63], v[82:83], v[26:27]
	v_pk_fma_f32 v[28:29], v[56:57], v[80:81], v[28:29]
	v_pk_fma_f32 v[30:31], v[58:59], v[82:83], v[30:31]
	v_lshlrev_b32_e32 v80, 16, v158
	v_and_b32_e32 v81, 0xffff0000, v158
	v_lshlrev_b32_e32 v82, 16, v159
	v_and_b32_e32 v83, 0xffff0000, v159
	v_pk_fma_f32 v[0:1], v[220:221], v[76:77], v[0:1]
	v_pk_fma_f32 v[2:3], v[222:223], v[78:79], v[2:3]
	v_pk_fma_f32 v[4:5], v[216:217], v[76:77], v[4:5]
	v_pk_fma_f32 v[6:7], v[218:219], v[78:79], v[6:7]
	v_pk_fma_f32 v[8:9], v[212:213], v[76:77], v[8:9]
	v_pk_fma_f32 v[10:11], v[214:215], v[78:79], v[10:11]
	v_pk_fma_f32 v[12:13], v[208:209], v[76:77], v[12:13]
	v_pk_fma_f32 v[14:15], v[210:211], v[78:79], v[14:15]
	v_pk_fma_f32 v[16:17], v[72:73], v[76:77], v[16:17]
	v_pk_fma_f32 v[18:19], v[74:75], v[78:79], v[18:19]
	v_pk_fma_f32 v[20:21], v[68:69], v[76:77], v[20:21]
	v_pk_fma_f32 v[22:23], v[70:71], v[78:79], v[22:23]
	v_pk_fma_f32 v[24:25], v[64:65], v[76:77], v[24:25]
	v_pk_fma_f32 v[26:27], v[66:67], v[78:79], v[26:27]
	v_pk_fma_f32 v[28:29], v[60:61], v[76:77], v[28:29]
	v_pk_fma_f32 v[30:31], v[62:63], v[78:79], v[30:31]
	v_lshlrev_b32_e32 v76, 16, v160
	v_and_b32_e32 v77, 0xffff0000, v160
	v_lshlrev_b32_e32 v78, 16, v161
	v_and_b32_e32 v79, 0xffff0000, v161
	v_pk_fma_f32 v[0:1], v[224:225], v[80:81], v[0:1]
	v_pk_fma_f32 v[2:3], v[226:227], v[82:83], v[2:3]
	v_pk_fma_f32 v[4:5], v[220:221], v[80:81], v[4:5]
	v_pk_fma_f32 v[6:7], v[222:223], v[82:83], v[6:7]
	v_pk_fma_f32 v[8:9], v[216:217], v[80:81], v[8:9]
	v_pk_fma_f32 v[10:11], v[218:219], v[82:83], v[10:11]
	v_pk_fma_f32 v[12:13], v[212:213], v[80:81], v[12:13]
	v_pk_fma_f32 v[14:15], v[214:215], v[82:83], v[14:15]
	v_pk_fma_f32 v[16:17], v[208:209], v[80:81], v[16:17]
	v_pk_fma_f32 v[18:19], v[210:211], v[82:83], v[18:19]
	v_pk_fma_f32 v[20:21], v[72:73], v[80:81], v[20:21]
	v_pk_fma_f32 v[22:23], v[74:75], v[82:83], v[22:23]
	v_pk_fma_f32 v[24:25], v[68:69], v[80:81], v[24:25]
	v_pk_fma_f32 v[26:27], v[70:71], v[82:83], v[26:27]
	v_pk_fma_f32 v[28:29], v[64:65], v[80:81], v[28:29]
	v_pk_fma_f32 v[30:31], v[66:67], v[82:83], v[30:31]
	v_lshlrev_b32_e32 v80, 16, v162
	v_and_b32_e32 v81, 0xffff0000, v162
	v_lshlrev_b32_e32 v82, 16, v163
	v_and_b32_e32 v83, 0xffff0000, v163
	v_pk_fma_f32 v[0:1], v[228:229], v[76:77], v[0:1]
	v_pk_fma_f32 v[2:3], v[230:231], v[78:79], v[2:3]
	v_pk_fma_f32 v[4:5], v[224:225], v[76:77], v[4:5]
	v_pk_fma_f32 v[6:7], v[226:227], v[78:79], v[6:7]
	v_pk_fma_f32 v[8:9], v[220:221], v[76:77], v[8:9]
	v_pk_fma_f32 v[10:11], v[222:223], v[78:79], v[10:11]
	v_pk_fma_f32 v[12:13], v[216:217], v[76:77], v[12:13]
	v_pk_fma_f32 v[14:15], v[218:219], v[78:79], v[14:15]
	v_pk_fma_f32 v[16:17], v[212:213], v[76:77], v[16:17]
	v_pk_fma_f32 v[18:19], v[214:215], v[78:79], v[18:19]
	v_pk_fma_f32 v[20:21], v[208:209], v[76:77], v[20:21]
	v_pk_fma_f32 v[22:23], v[210:211], v[78:79], v[22:23]
	v_pk_fma_f32 v[24:25], v[72:73], v[76:77], v[24:25]
	v_pk_fma_f32 v[26:27], v[74:75], v[78:79], v[26:27]
	v_pk_fma_f32 v[28:29], v[68:69], v[76:77], v[28:29]
	v_pk_fma_f32 v[30:31], v[70:71], v[78:79], v[30:31]
	v_lshlrev_b32_e32 v76, 16, v164
	v_and_b32_e32 v77, 0xffff0000, v164
	v_lshlrev_b32_e32 v78, 16, v165
	v_and_b32_e32 v79, 0xffff0000, v165
	v_pk_fma_f32 v[0:1], v[232:233], v[80:81], v[0:1]
	v_pk_fma_f32 v[2:3], v[234:235], v[82:83], v[2:3]
	v_pk_fma_f32 v[4:5], v[228:229], v[80:81], v[4:5]
	v_pk_fma_f32 v[6:7], v[230:231], v[82:83], v[6:7]
	v_pk_fma_f32 v[8:9], v[224:225], v[80:81], v[8:9]
	v_pk_fma_f32 v[10:11], v[226:227], v[82:83], v[10:11]
	v_pk_fma_f32 v[12:13], v[220:221], v[80:81], v[12:13]
	v_pk_fma_f32 v[14:15], v[222:223], v[82:83], v[14:15]
	v_pk_fma_f32 v[16:17], v[216:217], v[80:81], v[16:17]
	v_pk_fma_f32 v[18:19], v[218:219], v[82:83], v[18:19]
	v_pk_fma_f32 v[20:21], v[212:213], v[80:81], v[20:21]
	v_pk_fma_f32 v[22:23], v[214:215], v[82:83], v[22:23]
	v_pk_fma_f32 v[24:25], v[208:209], v[80:81], v[24:25]
	v_pk_fma_f32 v[26:27], v[210:211], v[82:83], v[26:27]
	v_pk_fma_f32 v[28:29], v[72:73], v[80:81], v[28:29]
	v_pk_fma_f32 v[30:31], v[74:75], v[82:83], v[30:31]
	v_lshlrev_b32_e32 v80, 16, v166
	v_and_b32_e32 v81, 0xffff0000, v166
	v_lshlrev_b32_e32 v82, 16, v167
	v_and_b32_e32 v83, 0xffff0000, v167
	v_pk_fma_f32 v[0:1], v[236:237], v[76:77], v[0:1]
	v_pk_fma_f32 v[2:3], v[238:239], v[78:79], v[2:3]
	v_pk_fma_f32 v[4:5], v[232:233], v[76:77], v[4:5]
	v_pk_fma_f32 v[6:7], v[234:235], v[78:79], v[6:7]
	v_pk_fma_f32 v[8:9], v[228:229], v[76:77], v[8:9]
	v_pk_fma_f32 v[10:11], v[230:231], v[78:79], v[10:11]
	v_pk_fma_f32 v[12:13], v[224:225], v[76:77], v[12:13]
	v_pk_fma_f32 v[14:15], v[226:227], v[78:79], v[14:15]
	v_pk_fma_f32 v[16:17], v[220:221], v[76:77], v[16:17]
	v_pk_fma_f32 v[18:19], v[222:223], v[78:79], v[18:19]
	v_pk_fma_f32 v[20:21], v[216:217], v[76:77], v[20:21]
	v_pk_fma_f32 v[22:23], v[218:219], v[78:79], v[22:23]
	v_pk_fma_f32 v[24:25], v[212:213], v[76:77], v[24:25]
	v_pk_fma_f32 v[26:27], v[214:215], v[78:79], v[26:27]
	v_pk_fma_f32 v[28:29], v[208:209], v[76:77], v[28:29]
	v_pk_fma_f32 v[30:31], v[210:211], v[78:79], v[30:31]
	v_lshlrev_b32_e32 v76, 16, v168
	v_and_b32_e32 v77, 0xffff0000, v168
	v_lshlrev_b32_e32 v78, 16, v169
	v_and_b32_e32 v79, 0xffff0000, v169
	ds_read_b128 v[32:35], v105 offset:19456
	ds_read_b128 v[36:39], v105 offset:20480
	ds_read_b128 v[40:43], v105 offset:21504
	ds_read_b128 v[44:47], v105 offset:22528
	ds_read_b128 v[48:51], v105 offset:23552
	ds_read_b128 v[52:55], v105 offset:24576
	ds_read_b128 v[56:59], v105 offset:25600
	ds_read_b128 v[60:63], v105 offset:26624
	ds_read_b128 v[64:67], v105 offset:27648
	ds_read_b128 v[68:71], v105 offset:28672
	ds_read_b128 v[72:75], v105 offset:29696
	ds_read_b128 v[208:211], v105 offset:30720
	s_waitcnt lgkmcnt(0)
	v_pk_fma_f32 v[0:1], v[32:33], v[80:81], v[0:1]
	v_pk_fma_f32 v[2:3], v[34:35], v[82:83], v[2:3]
	v_pk_fma_f32 v[4:5], v[236:237], v[80:81], v[4:5]
	v_pk_fma_f32 v[6:7], v[238:239], v[82:83], v[6:7]
	v_pk_fma_f32 v[8:9], v[232:233], v[80:81], v[8:9]
	v_pk_fma_f32 v[10:11], v[234:235], v[82:83], v[10:11]
	v_pk_fma_f32 v[12:13], v[228:229], v[80:81], v[12:13]
	v_pk_fma_f32 v[14:15], v[230:231], v[82:83], v[14:15]
	v_pk_fma_f32 v[16:17], v[224:225], v[80:81], v[16:17]
	v_pk_fma_f32 v[18:19], v[226:227], v[82:83], v[18:19]
	v_pk_fma_f32 v[20:21], v[220:221], v[80:81], v[20:21]
	v_pk_fma_f32 v[22:23], v[222:223], v[82:83], v[22:23]
	v_pk_fma_f32 v[24:25], v[216:217], v[80:81], v[24:25]
	v_pk_fma_f32 v[26:27], v[218:219], v[82:83], v[26:27]
	v_pk_fma_f32 v[28:29], v[212:213], v[80:81], v[28:29]
	v_pk_fma_f32 v[30:31], v[214:215], v[82:83], v[30:31]
	v_lshlrev_b32_e32 v80, 16, v170
	v_and_b32_e32 v81, 0xffff0000, v170
	v_lshlrev_b32_e32 v82, 16, v171
	v_and_b32_e32 v83, 0xffff0000, v171
	v_pk_fma_f32 v[0:1], v[36:37], v[76:77], v[0:1]
	v_pk_fma_f32 v[2:3], v[38:39], v[78:79], v[2:3]
	v_pk_fma_f32 v[4:5], v[32:33], v[76:77], v[4:5]
	v_pk_fma_f32 v[6:7], v[34:35], v[78:79], v[6:7]
	v_pk_fma_f32 v[8:9], v[236:237], v[76:77], v[8:9]
	v_pk_fma_f32 v[10:11], v[238:239], v[78:79], v[10:11]
	v_pk_fma_f32 v[12:13], v[232:233], v[76:77], v[12:13]
	v_pk_fma_f32 v[14:15], v[234:235], v[78:79], v[14:15]
	v_pk_fma_f32 v[16:17], v[228:229], v[76:77], v[16:17]
	v_pk_fma_f32 v[18:19], v[230:231], v[78:79], v[18:19]
	v_pk_fma_f32 v[20:21], v[224:225], v[76:77], v[20:21]
	v_pk_fma_f32 v[22:23], v[226:227], v[78:79], v[22:23]
	v_pk_fma_f32 v[24:25], v[220:221], v[76:77], v[24:25]
	v_pk_fma_f32 v[26:27], v[222:223], v[78:79], v[26:27]
	v_pk_fma_f32 v[28:29], v[216:217], v[76:77], v[28:29]
	v_pk_fma_f32 v[30:31], v[218:219], v[78:79], v[30:31]
	v_lshlrev_b32_e32 v76, 16, v172
	v_and_b32_e32 v77, 0xffff0000, v172
	v_lshlrev_b32_e32 v78, 16, v173
	v_and_b32_e32 v79, 0xffff0000, v173
	v_pk_fma_f32 v[0:1], v[40:41], v[80:81], v[0:1]
	v_pk_fma_f32 v[2:3], v[42:43], v[82:83], v[2:3]
	v_pk_fma_f32 v[4:5], v[36:37], v[80:81], v[4:5]
	v_pk_fma_f32 v[6:7], v[38:39], v[82:83], v[6:7]
	v_pk_fma_f32 v[8:9], v[32:33], v[80:81], v[8:9]
	v_pk_fma_f32 v[10:11], v[34:35], v[82:83], v[10:11]
	v_pk_fma_f32 v[12:13], v[236:237], v[80:81], v[12:13]
	v_pk_fma_f32 v[14:15], v[238:239], v[82:83], v[14:15]
	v_pk_fma_f32 v[16:17], v[232:233], v[80:81], v[16:17]
	v_pk_fma_f32 v[18:19], v[234:235], v[82:83], v[18:19]
	v_pk_fma_f32 v[20:21], v[228:229], v[80:81], v[20:21]
	v_pk_fma_f32 v[22:23], v[230:231], v[82:83], v[22:23]
	v_pk_fma_f32 v[24:25], v[224:225], v[80:81], v[24:25]
	v_pk_fma_f32 v[26:27], v[226:227], v[82:83], v[26:27]
	v_pk_fma_f32 v[28:29], v[220:221], v[80:81], v[28:29]
	v_pk_fma_f32 v[30:31], v[222:223], v[82:83], v[30:31]
	v_lshlrev_b32_e32 v80, 16, v174
	v_and_b32_e32 v81, 0xffff0000, v174
	v_lshlrev_b32_e32 v82, 16, v175
	v_and_b32_e32 v83, 0xffff0000, v175
	v_pk_fma_f32 v[0:1], v[44:45], v[76:77], v[0:1]
	v_pk_fma_f32 v[2:3], v[46:47], v[78:79], v[2:3]
	v_pk_fma_f32 v[4:5], v[40:41], v[76:77], v[4:5]
	v_pk_fma_f32 v[6:7], v[42:43], v[78:79], v[6:7]
	v_pk_fma_f32 v[8:9], v[36:37], v[76:77], v[8:9]
	v_pk_fma_f32 v[10:11], v[38:39], v[78:79], v[10:11]
	v_pk_fma_f32 v[12:13], v[32:33], v[76:77], v[12:13]
	v_pk_fma_f32 v[14:15], v[34:35], v[78:79], v[14:15]
	v_pk_fma_f32 v[16:17], v[236:237], v[76:77], v[16:17]
	v_pk_fma_f32 v[18:19], v[238:239], v[78:79], v[18:19]
	v_pk_fma_f32 v[20:21], v[232:233], v[76:77], v[20:21]
	v_pk_fma_f32 v[22:23], v[234:235], v[78:79], v[22:23]
	v_pk_fma_f32 v[24:25], v[228:229], v[76:77], v[24:25]
	v_pk_fma_f32 v[26:27], v[230:231], v[78:79], v[26:27]
	v_pk_fma_f32 v[28:29], v[224:225], v[76:77], v[28:29]
	v_pk_fma_f32 v[30:31], v[226:227], v[78:79], v[30:31]
	v_lshlrev_b32_e32 v76, 16, v176
	v_and_b32_e32 v77, 0xffff0000, v176
	v_lshlrev_b32_e32 v78, 16, v177
	v_and_b32_e32 v79, 0xffff0000, v177
	v_pk_fma_f32 v[0:1], v[48:49], v[80:81], v[0:1]
	v_pk_fma_f32 v[2:3], v[50:51], v[82:83], v[2:3]
	v_pk_fma_f32 v[4:5], v[44:45], v[80:81], v[4:5]
	v_pk_fma_f32 v[6:7], v[46:47], v[82:83], v[6:7]
	v_pk_fma_f32 v[8:9], v[40:41], v[80:81], v[8:9]
	v_pk_fma_f32 v[10:11], v[42:43], v[82:83], v[10:11]
	v_pk_fma_f32 v[12:13], v[36:37], v[80:81], v[12:13]
	v_pk_fma_f32 v[14:15], v[38:39], v[82:83], v[14:15]
	v_pk_fma_f32 v[16:17], v[32:33], v[80:81], v[16:17]
	v_pk_fma_f32 v[18:19], v[34:35], v[82:83], v[18:19]
	v_pk_fma_f32 v[20:21], v[236:237], v[80:81], v[20:21]
	v_pk_fma_f32 v[22:23], v[238:239], v[82:83], v[22:23]
	v_pk_fma_f32 v[24:25], v[232:233], v[80:81], v[24:25]
	v_pk_fma_f32 v[26:27], v[234:235], v[82:83], v[26:27]
	v_pk_fma_f32 v[28:29], v[228:229], v[80:81], v[28:29]
	v_pk_fma_f32 v[30:31], v[230:231], v[82:83], v[30:31]
	v_lshlrev_b32_e32 v80, 16, v178
	v_and_b32_e32 v81, 0xffff0000, v178
	v_lshlrev_b32_e32 v82, 16, v179
	v_and_b32_e32 v83, 0xffff0000, v179
	v_pk_fma_f32 v[0:1], v[52:53], v[76:77], v[0:1]
	v_pk_fma_f32 v[2:3], v[54:55], v[78:79], v[2:3]
	v_pk_fma_f32 v[4:5], v[48:49], v[76:77], v[4:5]
	v_pk_fma_f32 v[6:7], v[50:51], v[78:79], v[6:7]
	v_pk_fma_f32 v[8:9], v[44:45], v[76:77], v[8:9]
	v_pk_fma_f32 v[10:11], v[46:47], v[78:79], v[10:11]
	v_pk_fma_f32 v[12:13], v[40:41], v[76:77], v[12:13]
	v_pk_fma_f32 v[14:15], v[42:43], v[78:79], v[14:15]
	v_pk_fma_f32 v[16:17], v[36:37], v[76:77], v[16:17]
	v_pk_fma_f32 v[18:19], v[38:39], v[78:79], v[18:19]
	v_pk_fma_f32 v[20:21], v[32:33], v[76:77], v[20:21]
	v_pk_fma_f32 v[22:23], v[34:35], v[78:79], v[22:23]
	v_pk_fma_f32 v[24:25], v[236:237], v[76:77], v[24:25]
	v_pk_fma_f32 v[26:27], v[238:239], v[78:79], v[26:27]
	v_pk_fma_f32 v[28:29], v[232:233], v[76:77], v[28:29]
	v_pk_fma_f32 v[30:31], v[234:235], v[78:79], v[30:31]
	v_lshlrev_b32_e32 v76, 16, v180
	v_and_b32_e32 v77, 0xffff0000, v180
	v_lshlrev_b32_e32 v78, 16, v181
	v_and_b32_e32 v79, 0xffff0000, v181
	v_pk_fma_f32 v[0:1], v[56:57], v[80:81], v[0:1]
	v_pk_fma_f32 v[2:3], v[58:59], v[82:83], v[2:3]
	v_pk_fma_f32 v[4:5], v[52:53], v[80:81], v[4:5]
	v_pk_fma_f32 v[6:7], v[54:55], v[82:83], v[6:7]
	v_pk_fma_f32 v[8:9], v[48:49], v[80:81], v[8:9]
	v_pk_fma_f32 v[10:11], v[50:51], v[82:83], v[10:11]
	v_pk_fma_f32 v[12:13], v[44:45], v[80:81], v[12:13]
	v_pk_fma_f32 v[14:15], v[46:47], v[82:83], v[14:15]
	v_pk_fma_f32 v[16:17], v[40:41], v[80:81], v[16:17]
	v_pk_fma_f32 v[18:19], v[42:43], v[82:83], v[18:19]
	v_pk_fma_f32 v[20:21], v[36:37], v[80:81], v[20:21]
	v_pk_fma_f32 v[22:23], v[38:39], v[82:83], v[22:23]
	v_pk_fma_f32 v[24:25], v[32:33], v[80:81], v[24:25]
	v_pk_fma_f32 v[26:27], v[34:35], v[82:83], v[26:27]
	v_pk_fma_f32 v[28:29], v[236:237], v[80:81], v[28:29]
	v_pk_fma_f32 v[30:31], v[238:239], v[82:83], v[30:31]
	v_lshlrev_b32_e32 v80, 16, v182
	v_and_b32_e32 v81, 0xffff0000, v182
	v_lshlrev_b32_e32 v82, 16, v183
	v_and_b32_e32 v83, 0xffff0000, v183
	v_pk_fma_f32 v[0:1], v[60:61], v[76:77], v[0:1]
	v_pk_fma_f32 v[2:3], v[62:63], v[78:79], v[2:3]
	v_pk_fma_f32 v[4:5], v[56:57], v[76:77], v[4:5]
	v_pk_fma_f32 v[6:7], v[58:59], v[78:79], v[6:7]
	v_pk_fma_f32 v[8:9], v[52:53], v[76:77], v[8:9]
	v_pk_fma_f32 v[10:11], v[54:55], v[78:79], v[10:11]
	v_pk_fma_f32 v[12:13], v[48:49], v[76:77], v[12:13]
	v_pk_fma_f32 v[14:15], v[50:51], v[78:79], v[14:15]
	v_pk_fma_f32 v[16:17], v[44:45], v[76:77], v[16:17]
	v_pk_fma_f32 v[18:19], v[46:47], v[78:79], v[18:19]
	v_pk_fma_f32 v[20:21], v[40:41], v[76:77], v[20:21]
	v_pk_fma_f32 v[22:23], v[42:43], v[78:79], v[22:23]
	v_pk_fma_f32 v[24:25], v[36:37], v[76:77], v[24:25]
	v_pk_fma_f32 v[26:27], v[38:39], v[78:79], v[26:27]
	v_pk_fma_f32 v[28:29], v[32:33], v[76:77], v[28:29]
	v_pk_fma_f32 v[30:31], v[34:35], v[78:79], v[30:31]
	v_lshlrev_b32_e32 v76, 16, v184
	v_and_b32_e32 v77, 0xffff0000, v184
	v_lshlrev_b32_e32 v78, 16, v185
	v_and_b32_e32 v79, 0xffff0000, v185
	v_pk_fma_f32 v[0:1], v[64:65], v[80:81], v[0:1]
	v_pk_fma_f32 v[2:3], v[66:67], v[82:83], v[2:3]
	v_pk_fma_f32 v[4:5], v[60:61], v[80:81], v[4:5]
	v_pk_fma_f32 v[6:7], v[62:63], v[82:83], v[6:7]
	v_pk_fma_f32 v[8:9], v[56:57], v[80:81], v[8:9]
	v_pk_fma_f32 v[10:11], v[58:59], v[82:83], v[10:11]
	v_pk_fma_f32 v[12:13], v[52:53], v[80:81], v[12:13]
	v_pk_fma_f32 v[14:15], v[54:55], v[82:83], v[14:15]
	v_pk_fma_f32 v[16:17], v[48:49], v[80:81], v[16:17]
	v_pk_fma_f32 v[18:19], v[50:51], v[82:83], v[18:19]
	v_pk_fma_f32 v[20:21], v[44:45], v[80:81], v[20:21]
	v_pk_fma_f32 v[22:23], v[46:47], v[82:83], v[22:23]
	v_pk_fma_f32 v[24:25], v[40:41], v[80:81], v[24:25]
	v_pk_fma_f32 v[26:27], v[42:43], v[82:83], v[26:27]
	v_pk_fma_f32 v[28:29], v[36:37], v[80:81], v[28:29]
	v_pk_fma_f32 v[30:31], v[38:39], v[82:83], v[30:31]
	v_lshlrev_b32_e32 v80, 16, v186
	v_and_b32_e32 v81, 0xffff0000, v186
	v_lshlrev_b32_e32 v82, 16, v187
	v_and_b32_e32 v83, 0xffff0000, v187
	v_pk_fma_f32 v[0:1], v[68:69], v[76:77], v[0:1]
	v_pk_fma_f32 v[2:3], v[70:71], v[78:79], v[2:3]
	v_pk_fma_f32 v[4:5], v[64:65], v[76:77], v[4:5]
	v_pk_fma_f32 v[6:7], v[66:67], v[78:79], v[6:7]
	v_pk_fma_f32 v[8:9], v[60:61], v[76:77], v[8:9]
	v_pk_fma_f32 v[10:11], v[62:63], v[78:79], v[10:11]
	v_pk_fma_f32 v[12:13], v[56:57], v[76:77], v[12:13]
	v_pk_fma_f32 v[14:15], v[58:59], v[78:79], v[14:15]
	v_pk_fma_f32 v[16:17], v[52:53], v[76:77], v[16:17]
	v_pk_fma_f32 v[18:19], v[54:55], v[78:79], v[18:19]
	v_pk_fma_f32 v[20:21], v[48:49], v[76:77], v[20:21]
	v_pk_fma_f32 v[22:23], v[50:51], v[78:79], v[22:23]
	v_pk_fma_f32 v[24:25], v[44:45], v[76:77], v[24:25]
	v_pk_fma_f32 v[26:27], v[46:47], v[78:79], v[26:27]
	v_pk_fma_f32 v[28:29], v[40:41], v[76:77], v[28:29]
	v_pk_fma_f32 v[30:31], v[42:43], v[78:79], v[30:31]
	v_lshlrev_b32_e32 v76, 16, v188
	v_and_b32_e32 v77, 0xffff0000, v188
	v_lshlrev_b32_e32 v78, 16, v189
	v_and_b32_e32 v79, 0xffff0000, v189
	v_pk_fma_f32 v[0:1], v[72:73], v[80:81], v[0:1]
	v_pk_fma_f32 v[2:3], v[74:75], v[82:83], v[2:3]
	v_pk_fma_f32 v[4:5], v[68:69], v[80:81], v[4:5]
	v_pk_fma_f32 v[6:7], v[70:71], v[82:83], v[6:7]
	v_pk_fma_f32 v[8:9], v[64:65], v[80:81], v[8:9]
	v_pk_fma_f32 v[10:11], v[66:67], v[82:83], v[10:11]
	v_pk_fma_f32 v[12:13], v[60:61], v[80:81], v[12:13]
	v_pk_fma_f32 v[14:15], v[62:63], v[82:83], v[14:15]
	v_pk_fma_f32 v[16:17], v[56:57], v[80:81], v[16:17]
	v_pk_fma_f32 v[18:19], v[58:59], v[82:83], v[18:19]
	v_pk_fma_f32 v[20:21], v[52:53], v[80:81], v[20:21]
	v_pk_fma_f32 v[22:23], v[54:55], v[82:83], v[22:23]
	v_pk_fma_f32 v[24:25], v[48:49], v[80:81], v[24:25]
	v_pk_fma_f32 v[26:27], v[50:51], v[82:83], v[26:27]
	v_pk_fma_f32 v[28:29], v[44:45], v[80:81], v[28:29]
	v_pk_fma_f32 v[30:31], v[46:47], v[82:83], v[30:31]
	v_lshlrev_b32_e32 v80, 16, v190
	v_and_b32_e32 v81, 0xffff0000, v190
	v_lshlrev_b32_e32 v82, 16, v191
	v_and_b32_e32 v83, 0xffff0000, v191
	v_pk_fma_f32 v[0:1], v[208:209], v[76:77], v[0:1]
	v_pk_fma_f32 v[2:3], v[210:211], v[78:79], v[2:3]
	v_pk_fma_f32 v[4:5], v[72:73], v[76:77], v[4:5]
	v_pk_fma_f32 v[6:7], v[74:75], v[78:79], v[6:7]
	v_pk_fma_f32 v[8:9], v[68:69], v[76:77], v[8:9]
	v_pk_fma_f32 v[10:11], v[70:71], v[78:79], v[10:11]
	v_pk_fma_f32 v[12:13], v[64:65], v[76:77], v[12:13]
	v_pk_fma_f32 v[14:15], v[66:67], v[78:79], v[14:15]
	v_pk_fma_f32 v[16:17], v[60:61], v[76:77], v[16:17]
	v_pk_fma_f32 v[18:19], v[62:63], v[78:79], v[18:19]
	v_pk_fma_f32 v[20:21], v[56:57], v[76:77], v[20:21]
	v_pk_fma_f32 v[22:23], v[58:59], v[78:79], v[22:23]
	v_pk_fma_f32 v[24:25], v[52:53], v[76:77], v[24:25]
	v_pk_fma_f32 v[26:27], v[54:55], v[78:79], v[26:27]
	v_pk_fma_f32 v[28:29], v[48:49], v[76:77], v[28:29]
	v_pk_fma_f32 v[30:31], v[50:51], v[78:79], v[30:31]
	v_lshlrev_b32_e32 v76, 16, v192
	v_and_b32_e32 v77, 0xffff0000, v192
	v_lshlrev_b32_e32 v78, 16, v193
	v_and_b32_e32 v79, 0xffff0000, v193
	v_pk_fma_f32 v[4:5], v[208:209], v[80:81], v[4:5]
	v_pk_fma_f32 v[6:7], v[210:211], v[82:83], v[6:7]
	v_pk_fma_f32 v[8:9], v[72:73], v[80:81], v[8:9]
	v_pk_fma_f32 v[10:11], v[74:75], v[82:83], v[10:11]
	v_pk_fma_f32 v[12:13], v[68:69], v[80:81], v[12:13]
	v_pk_fma_f32 v[14:15], v[70:71], v[82:83], v[14:15]
	v_pk_fma_f32 v[16:17], v[64:65], v[80:81], v[16:17]
	v_pk_fma_f32 v[18:19], v[66:67], v[82:83], v[18:19]
	v_pk_fma_f32 v[20:21], v[60:61], v[80:81], v[20:21]
	v_pk_fma_f32 v[22:23], v[62:63], v[82:83], v[22:23]
	v_pk_fma_f32 v[24:25], v[56:57], v[80:81], v[24:25]
	v_pk_fma_f32 v[26:27], v[58:59], v[82:83], v[26:27]
	v_pk_fma_f32 v[28:29], v[52:53], v[80:81], v[28:29]
	v_pk_fma_f32 v[30:31], v[54:55], v[82:83], v[30:31]
	v_lshlrev_b32_e32 v80, 16, v194
	v_and_b32_e32 v81, 0xffff0000, v194
	v_lshlrev_b32_e32 v82, 16, v195
	v_and_b32_e32 v83, 0xffff0000, v195
	v_pk_fma_f32 v[8:9], v[208:209], v[76:77], v[8:9]
	v_pk_fma_f32 v[10:11], v[210:211], v[78:79], v[10:11]
	v_pk_fma_f32 v[12:13], v[72:73], v[76:77], v[12:13]
	v_pk_fma_f32 v[14:15], v[74:75], v[78:79], v[14:15]
	v_pk_fma_f32 v[16:17], v[68:69], v[76:77], v[16:17]
	v_pk_fma_f32 v[18:19], v[70:71], v[78:79], v[18:19]
	v_pk_fma_f32 v[20:21], v[64:65], v[76:77], v[20:21]
	v_pk_fma_f32 v[22:23], v[66:67], v[78:79], v[22:23]
	v_pk_fma_f32 v[24:25], v[60:61], v[76:77], v[24:25]
	v_pk_fma_f32 v[26:27], v[62:63], v[78:79], v[26:27]
	v_pk_fma_f32 v[28:29], v[56:57], v[76:77], v[28:29]
	v_pk_fma_f32 v[30:31], v[58:59], v[78:79], v[30:31]
	v_lshlrev_b32_e32 v76, 16, v196
	v_and_b32_e32 v77, 0xffff0000, v196
	v_lshlrev_b32_e32 v78, 16, v197
	v_and_b32_e32 v79, 0xffff0000, v197
	v_pk_fma_f32 v[12:13], v[208:209], v[80:81], v[12:13]
	v_pk_fma_f32 v[14:15], v[210:211], v[82:83], v[14:15]
	v_pk_fma_f32 v[16:17], v[72:73], v[80:81], v[16:17]
	v_pk_fma_f32 v[18:19], v[74:75], v[82:83], v[18:19]
	v_pk_fma_f32 v[20:21], v[68:69], v[80:81], v[20:21]
	v_pk_fma_f32 v[22:23], v[70:71], v[82:83], v[22:23]
	v_pk_fma_f32 v[24:25], v[64:65], v[80:81], v[24:25]
	v_pk_fma_f32 v[26:27], v[66:67], v[82:83], v[26:27]
	v_pk_fma_f32 v[28:29], v[60:61], v[80:81], v[28:29]
	v_pk_fma_f32 v[30:31], v[62:63], v[82:83], v[30:31]
	v_lshlrev_b32_e32 v80, 16, v200
	v_and_b32_e32 v81, 0xffff0000, v200
	v_lshlrev_b32_e32 v82, 16, v201
	v_and_b32_e32 v83, 0xffff0000, v201
	v_pk_fma_f32 v[16:17], v[208:209], v[76:77], v[16:17]
	v_pk_fma_f32 v[18:19], v[210:211], v[78:79], v[18:19]
	v_pk_fma_f32 v[20:21], v[72:73], v[76:77], v[20:21]
	v_pk_fma_f32 v[22:23], v[74:75], v[78:79], v[22:23]
	v_pk_fma_f32 v[24:25], v[68:69], v[76:77], v[24:25]
	v_pk_fma_f32 v[26:27], v[70:71], v[78:79], v[26:27]
	v_pk_fma_f32 v[28:29], v[64:65], v[76:77], v[28:29]
	v_pk_fma_f32 v[30:31], v[66:67], v[78:79], v[30:31]
	v_lshlrev_b32_e32 v76, 16, v202
	v_and_b32_e32 v77, 0xffff0000, v202
	v_lshlrev_b32_e32 v78, 16, v203
	v_and_b32_e32 v79, 0xffff0000, v203
	v_pk_fma_f32 v[20:21], v[208:209], v[80:81], v[20:21]
	v_pk_fma_f32 v[22:23], v[210:211], v[82:83], v[22:23]
	v_pk_fma_f32 v[24:25], v[72:73], v[80:81], v[24:25]
	v_pk_fma_f32 v[26:27], v[74:75], v[82:83], v[26:27]
	v_pk_fma_f32 v[28:29], v[68:69], v[80:81], v[28:29]
	v_pk_fma_f32 v[30:31], v[70:71], v[82:83], v[30:31]
	v_lshlrev_b32_e32 v80, 16, v204
	v_and_b32_e32 v81, 0xffff0000, v204
	v_lshlrev_b32_e32 v82, 16, v205
	v_and_b32_e32 v83, 0xffff0000, v205
	v_pk_fma_f32 v[24:25], v[208:209], v[76:77], v[24:25]
	v_pk_fma_f32 v[26:27], v[210:211], v[78:79], v[26:27]
	v_pk_fma_f32 v[28:29], v[72:73], v[76:77], v[28:29]
	v_pk_fma_f32 v[30:31], v[74:75], v[78:79], v[30:31]
	v_pk_fma_f32 v[28:29], v[208:209], v[80:81], v[28:29]
	v_pk_fma_f32 v[30:31], v[210:211], v[82:83], v[30:31]
	v_add_f32_e32 v124, v0, v1
	v_add_f32_e32 v125, v2, v3
	v_add_f32_e32 v107, v124, v125
	v_add_f32_e32 v124, v4, v5
	v_add_f32_e32 v125, v6, v7
	v_add_f32_e32 v108, v124, v125
	v_add_f32_e32 v124, v8, v9
	v_add_f32_e32 v125, v10, v11
	v_add_f32_e32 v109, v124, v125
	v_add_f32_e32 v124, v12, v13
	v_add_f32_e32 v125, v14, v15
	v_add_f32_e32 v110, v124, v125
	v_add_f32_e32 v124, v16, v17
	v_add_f32_e32 v125, v18, v19
	v_add_f32_e32 v111, v124, v125
	v_add_f32_e32 v124, v20, v21
	v_add_f32_e32 v125, v22, v23
	v_add_f32_e32 v112, v124, v125
	v_add_f32_e32 v124, v24, v25
	v_add_f32_e32 v125, v26, v27
	v_add_f32_e32 v113, v124, v125
	v_add_f32_e32 v124, v28, v29
	v_add_f32_e32 v125, v30, v31
	v_add_f32_e32 v114, v124, v125
	ds_bpermute_b32 v115, v98, v107
	ds_bpermute_b32 v116, v98, v108
	ds_bpermute_b32 v117, v98, v109
	ds_bpermute_b32 v118, v98, v110
	ds_bpermute_b32 v119, v98, v111
	ds_bpermute_b32 v120, v98, v112
	ds_bpermute_b32 v121, v98, v113
	ds_bpermute_b32 v122, v98, v114
	s_waitcnt lgkmcnt(7)
	v_add_f32_e32 v107, v107, v115
	s_waitcnt lgkmcnt(6)
	v_add_f32_e32 v108, v108, v116
	s_waitcnt lgkmcnt(5)
	v_add_f32_e32 v109, v109, v117
	s_waitcnt lgkmcnt(4)
	v_add_f32_e32 v110, v110, v118
	s_waitcnt lgkmcnt(3)
	v_add_f32_e32 v111, v111, v119
	s_waitcnt lgkmcnt(2)
	v_add_f32_e32 v112, v112, v120
	s_waitcnt lgkmcnt(1)
	v_add_f32_e32 v113, v113, v121
	s_waitcnt lgkmcnt(0)
	v_add_f32_e32 v114, v114, v122
	ds_bpermute_b32 v115, v99, v107
	ds_bpermute_b32 v116, v99, v108
	ds_bpermute_b32 v117, v99, v109
	ds_bpermute_b32 v118, v99, v110
	ds_bpermute_b32 v119, v99, v111
	ds_bpermute_b32 v120, v99, v112
	ds_bpermute_b32 v121, v99, v113
	ds_bpermute_b32 v122, v99, v114
	s_waitcnt lgkmcnt(7)
	v_add_f32_e32 v107, v107, v115
	s_waitcnt lgkmcnt(6)
	v_add_f32_e32 v108, v108, v116
	s_waitcnt lgkmcnt(5)
	v_add_f32_e32 v109, v109, v117
	s_waitcnt lgkmcnt(4)
	v_add_f32_e32 v110, v110, v118
	s_waitcnt lgkmcnt(3)
	v_add_f32_e32 v111, v111, v119
	s_waitcnt lgkmcnt(2)
	v_add_f32_e32 v112, v112, v120
	s_waitcnt lgkmcnt(1)
	v_add_f32_e32 v113, v113, v121
	s_waitcnt lgkmcnt(0)
	v_add_f32_e32 v114, v114, v122
	ds_bpermute_b32 v115, v100, v107
	ds_bpermute_b32 v116, v100, v108
	ds_bpermute_b32 v117, v100, v109
	ds_bpermute_b32 v118, v100, v110
	ds_bpermute_b32 v119, v100, v111
	ds_bpermute_b32 v120, v100, v112
	ds_bpermute_b32 v121, v100, v113
	ds_bpermute_b32 v122, v100, v114
	s_waitcnt lgkmcnt(7)
	v_add_f32_e32 v107, v107, v115
	s_waitcnt lgkmcnt(6)
	v_add_f32_e32 v108, v108, v116
	s_waitcnt lgkmcnt(5)
	v_add_f32_e32 v109, v109, v117
	s_waitcnt lgkmcnt(4)
	v_add_f32_e32 v110, v110, v118
	s_waitcnt lgkmcnt(3)
	v_add_f32_e32 v111, v111, v119
	s_waitcnt lgkmcnt(2)
	v_add_f32_e32 v112, v112, v120
	s_waitcnt lgkmcnt(1)
	v_add_f32_e32 v113, v113, v121
	s_waitcnt lgkmcnt(0)
	v_add_f32_e32 v114, v114, v122
	ds_bpermute_b32 v115, v101, v107
	ds_bpermute_b32 v116, v101, v108
	ds_bpermute_b32 v117, v101, v109
	ds_bpermute_b32 v118, v101, v110
	ds_bpermute_b32 v119, v101, v111
	ds_bpermute_b32 v120, v101, v112
	ds_bpermute_b32 v121, v101, v113
	ds_bpermute_b32 v122, v101, v114
	s_waitcnt lgkmcnt(7)
	v_add_f32_e32 v107, v107, v115
	s_waitcnt lgkmcnt(6)
	v_add_f32_e32 v108, v108, v116
	s_waitcnt lgkmcnt(5)
	v_add_f32_e32 v109, v109, v117
	s_waitcnt lgkmcnt(4)
	v_add_f32_e32 v110, v110, v118
	s_waitcnt lgkmcnt(3)
	v_add_f32_e32 v111, v111, v119
	s_waitcnt lgkmcnt(2)
	v_add_f32_e32 v112, v112, v120
	s_waitcnt lgkmcnt(1)
	v_add_f32_e32 v113, v113, v121
	s_waitcnt lgkmcnt(0)
	v_add_f32_e32 v114, v114, v122
	ds_bpermute_b32 v115, v102, v107
	ds_bpermute_b32 v116, v102, v108
	ds_bpermute_b32 v117, v102, v109
	ds_bpermute_b32 v118, v102, v110
	ds_bpermute_b32 v119, v102, v111
	ds_bpermute_b32 v120, v102, v112
	ds_bpermute_b32 v121, v102, v113
	ds_bpermute_b32 v122, v102, v114
	s_waitcnt lgkmcnt(7)
	v_add_f32_e32 v107, v107, v115
	s_waitcnt lgkmcnt(6)
	v_add_f32_e32 v108, v108, v116
	s_waitcnt lgkmcnt(5)
	v_add_f32_e32 v109, v109, v117
	s_waitcnt lgkmcnt(4)
	v_add_f32_e32 v110, v110, v118
	s_waitcnt lgkmcnt(3)
	v_add_f32_e32 v111, v111, v119
	s_waitcnt lgkmcnt(2)
	v_add_f32_e32 v112, v112, v120
	s_waitcnt lgkmcnt(1)
	v_add_f32_e32 v113, v113, v121
	s_waitcnt lgkmcnt(0)
	v_add_f32_e32 v114, v114, v122
	ds_bpermute_b32 v115, v103, v107
	ds_bpermute_b32 v116, v103, v108
	ds_bpermute_b32 v117, v103, v109
	ds_bpermute_b32 v118, v103, v110
	ds_bpermute_b32 v119, v103, v111
	ds_bpermute_b32 v120, v103, v112
	ds_bpermute_b32 v121, v103, v113
	ds_bpermute_b32 v122, v103, v114
	s_waitcnt lgkmcnt(7)
	v_add_f32_e32 v107, v107, v115
	s_waitcnt lgkmcnt(6)
	v_add_f32_e32 v108, v108, v116
	s_waitcnt lgkmcnt(5)
	v_add_f32_e32 v109, v109, v117
	s_waitcnt lgkmcnt(4)
	v_add_f32_e32 v110, v110, v118
	s_waitcnt lgkmcnt(3)
	v_add_f32_e32 v111, v111, v119
	s_waitcnt lgkmcnt(2)
	v_add_f32_e32 v112, v112, v120
	s_waitcnt lgkmcnt(1)
	v_add_f32_e32 v113, v113, v121
	s_waitcnt lgkmcnt(0)
	v_add_f32_e32 v114, v114, v122
	v_mul_f32_e32 v124, 0x3b800000, v107
	v_sub_f32_e32 v0, v0, v124
	v_sub_f32_e32 v1, v1, v124
	v_sub_f32_e32 v2, v2, v124
	v_sub_f32_e32 v3, v3, v124
	v_mul_f32_e32 v125, v0, v0
	v_fmac_f32_e32 v125, v1, v1
	v_mul_f32_e32 v126, v2, v2
	v_fmac_f32_e32 v126, v3, v3
	v_add_f32_e32 v107, v125, v126
	v_mul_f32_e32 v124, 0x3b800000, v108
	v_sub_f32_e32 v4, v4, v124
	v_sub_f32_e32 v5, v5, v124
	v_sub_f32_e32 v6, v6, v124
	v_sub_f32_e32 v7, v7, v124
	v_mul_f32_e32 v125, v4, v4
	v_fmac_f32_e32 v125, v5, v5
	v_mul_f32_e32 v126, v6, v6
	v_fmac_f32_e32 v126, v7, v7
	v_add_f32_e32 v108, v125, v126
	v_mul_f32_e32 v124, 0x3b800000, v109
	v_sub_f32_e32 v8, v8, v124
	v_sub_f32_e32 v9, v9, v124
	v_sub_f32_e32 v10, v10, v124
	v_sub_f32_e32 v11, v11, v124
	v_mul_f32_e32 v125, v8, v8
	v_fmac_f32_e32 v125, v9, v9
	v_mul_f32_e32 v126, v10, v10
	v_fmac_f32_e32 v126, v11, v11
	v_add_f32_e32 v109, v125, v126
	v_mul_f32_e32 v124, 0x3b800000, v110
	v_sub_f32_e32 v12, v12, v124
	v_sub_f32_e32 v13, v13, v124
	v_sub_f32_e32 v14, v14, v124
	v_sub_f32_e32 v15, v15, v124
	v_mul_f32_e32 v125, v12, v12
	v_fmac_f32_e32 v125, v13, v13
	v_mul_f32_e32 v126, v14, v14
	v_fmac_f32_e32 v126, v15, v15
	v_add_f32_e32 v110, v125, v126
	v_mul_f32_e32 v124, 0x3b800000, v111
	v_sub_f32_e32 v16, v16, v124
	v_sub_f32_e32 v17, v17, v124
	v_sub_f32_e32 v18, v18, v124
	v_sub_f32_e32 v19, v19, v124
	v_mul_f32_e32 v125, v16, v16
	v_fmac_f32_e32 v125, v17, v17
	v_mul_f32_e32 v126, v18, v18
	v_fmac_f32_e32 v126, v19, v19
	v_add_f32_e32 v111, v125, v126
	v_mul_f32_e32 v124, 0x3b800000, v112
	v_sub_f32_e32 v20, v20, v124
	v_sub_f32_e32 v21, v21, v124
	v_sub_f32_e32 v22, v22, v124
	v_sub_f32_e32 v23, v23, v124
	v_mul_f32_e32 v125, v20, v20
	v_fmac_f32_e32 v125, v21, v21
	v_mul_f32_e32 v126, v22, v22
	v_fmac_f32_e32 v126, v23, v23
	v_add_f32_e32 v112, v125, v126
	v_mul_f32_e32 v124, 0x3b800000, v113
	v_sub_f32_e32 v24, v24, v124
	v_sub_f32_e32 v25, v25, v124
	v_sub_f32_e32 v26, v26, v124
	v_sub_f32_e32 v27, v27, v124
	v_mul_f32_e32 v125, v24, v24
	v_fmac_f32_e32 v125, v25, v25
	v_mul_f32_e32 v126, v26, v26
	v_fmac_f32_e32 v126, v27, v27
	v_add_f32_e32 v113, v125, v126
	v_mul_f32_e32 v124, 0x3b800000, v114
	v_sub_f32_e32 v28, v28, v124
	v_sub_f32_e32 v29, v29, v124
	v_sub_f32_e32 v30, v30, v124
	v_sub_f32_e32 v31, v31, v124
	v_mul_f32_e32 v125, v28, v28
	v_fmac_f32_e32 v125, v29, v29
	v_mul_f32_e32 v126, v30, v30
	v_fmac_f32_e32 v126, v31, v31
	v_add_f32_e32 v114, v125, v126
	ds_bpermute_b32 v115, v98, v107
	ds_bpermute_b32 v116, v98, v108
	ds_bpermute_b32 v117, v98, v109
	ds_bpermute_b32 v118, v98, v110
	ds_bpermute_b32 v119, v98, v111
	ds_bpermute_b32 v120, v98, v112
	ds_bpermute_b32 v121, v98, v113
	ds_bpermute_b32 v122, v98, v114
	s_waitcnt lgkmcnt(7)
	v_add_f32_e32 v107, v107, v115
	s_waitcnt lgkmcnt(6)
	v_add_f32_e32 v108, v108, v116
	s_waitcnt lgkmcnt(5)
	v_add_f32_e32 v109, v109, v117
	s_waitcnt lgkmcnt(4)
	v_add_f32_e32 v110, v110, v118
	s_waitcnt lgkmcnt(3)
	v_add_f32_e32 v111, v111, v119
	s_waitcnt lgkmcnt(2)
	v_add_f32_e32 v112, v112, v120
	s_waitcnt lgkmcnt(1)
	v_add_f32_e32 v113, v113, v121
	s_waitcnt lgkmcnt(0)
	v_add_f32_e32 v114, v114, v122
	ds_bpermute_b32 v115, v99, v107
	ds_bpermute_b32 v116, v99, v108
	ds_bpermute_b32 v117, v99, v109
	ds_bpermute_b32 v118, v99, v110
	ds_bpermute_b32 v119, v99, v111
	ds_bpermute_b32 v120, v99, v112
	ds_bpermute_b32 v121, v99, v113
	ds_bpermute_b32 v122, v99, v114
	s_waitcnt lgkmcnt(7)
	v_add_f32_e32 v107, v107, v115
	s_waitcnt lgkmcnt(6)
	v_add_f32_e32 v108, v108, v116
	s_waitcnt lgkmcnt(5)
	v_add_f32_e32 v109, v109, v117
	s_waitcnt lgkmcnt(4)
	v_add_f32_e32 v110, v110, v118
	s_waitcnt lgkmcnt(3)
	v_add_f32_e32 v111, v111, v119
	s_waitcnt lgkmcnt(2)
	v_add_f32_e32 v112, v112, v120
	s_waitcnt lgkmcnt(1)
	v_add_f32_e32 v113, v113, v121
	s_waitcnt lgkmcnt(0)
	v_add_f32_e32 v114, v114, v122
	ds_bpermute_b32 v115, v100, v107
	ds_bpermute_b32 v116, v100, v108
	ds_bpermute_b32 v117, v100, v109
	ds_bpermute_b32 v118, v100, v110
	ds_bpermute_b32 v119, v100, v111
	ds_bpermute_b32 v120, v100, v112
	ds_bpermute_b32 v121, v100, v113
	ds_bpermute_b32 v122, v100, v114
	s_waitcnt lgkmcnt(7)
	v_add_f32_e32 v107, v107, v115
	s_waitcnt lgkmcnt(6)
	v_add_f32_e32 v108, v108, v116
	s_waitcnt lgkmcnt(5)
	v_add_f32_e32 v109, v109, v117
	s_waitcnt lgkmcnt(4)
	v_add_f32_e32 v110, v110, v118
	s_waitcnt lgkmcnt(3)
	v_add_f32_e32 v111, v111, v119
	s_waitcnt lgkmcnt(2)
	v_add_f32_e32 v112, v112, v120
	s_waitcnt lgkmcnt(1)
	v_add_f32_e32 v113, v113, v121
	s_waitcnt lgkmcnt(0)
	v_add_f32_e32 v114, v114, v122
	ds_bpermute_b32 v115, v101, v107
	ds_bpermute_b32 v116, v101, v108
	ds_bpermute_b32 v117, v101, v109
	ds_bpermute_b32 v118, v101, v110
	ds_bpermute_b32 v119, v101, v111
	ds_bpermute_b32 v120, v101, v112
	ds_bpermute_b32 v121, v101, v113
	ds_bpermute_b32 v122, v101, v114
	s_waitcnt lgkmcnt(7)
	v_add_f32_e32 v107, v107, v115
	s_waitcnt lgkmcnt(6)
	v_add_f32_e32 v108, v108, v116
	s_waitcnt lgkmcnt(5)
	v_add_f32_e32 v109, v109, v117
	s_waitcnt lgkmcnt(4)
	v_add_f32_e32 v110, v110, v118
	s_waitcnt lgkmcnt(3)
	v_add_f32_e32 v111, v111, v119
	s_waitcnt lgkmcnt(2)
	v_add_f32_e32 v112, v112, v120
	s_waitcnt lgkmcnt(1)
	v_add_f32_e32 v113, v113, v121
	s_waitcnt lgkmcnt(0)
	v_add_f32_e32 v114, v114, v122
	ds_bpermute_b32 v115, v102, v107
	ds_bpermute_b32 v116, v102, v108
	ds_bpermute_b32 v117, v102, v109
	ds_bpermute_b32 v118, v102, v110
	ds_bpermute_b32 v119, v102, v111
	ds_bpermute_b32 v120, v102, v112
	ds_bpermute_b32 v121, v102, v113
	ds_bpermute_b32 v122, v102, v114
	s_waitcnt lgkmcnt(7)
	v_add_f32_e32 v107, v107, v115
	s_waitcnt lgkmcnt(6)
	v_add_f32_e32 v108, v108, v116
	s_waitcnt lgkmcnt(5)
	v_add_f32_e32 v109, v109, v117
	s_waitcnt lgkmcnt(4)
	v_add_f32_e32 v110, v110, v118
	s_waitcnt lgkmcnt(3)
	v_add_f32_e32 v111, v111, v119
	s_waitcnt lgkmcnt(2)
	v_add_f32_e32 v112, v112, v120
	s_waitcnt lgkmcnt(1)
	v_add_f32_e32 v113, v113, v121
	s_waitcnt lgkmcnt(0)
	v_add_f32_e32 v114, v114, v122
	ds_bpermute_b32 v115, v103, v107
	ds_bpermute_b32 v116, v103, v108
	ds_bpermute_b32 v117, v103, v109
	ds_bpermute_b32 v118, v103, v110
	ds_bpermute_b32 v119, v103, v111
	ds_bpermute_b32 v120, v103, v112
	ds_bpermute_b32 v121, v103, v113
	ds_bpermute_b32 v122, v103, v114
	s_waitcnt lgkmcnt(7)
	v_add_f32_e32 v107, v107, v115
	s_waitcnt lgkmcnt(6)
	v_add_f32_e32 v108, v108, v116
	s_waitcnt lgkmcnt(5)
	v_add_f32_e32 v109, v109, v117
	s_waitcnt lgkmcnt(4)
	v_add_f32_e32 v110, v110, v118
	s_waitcnt lgkmcnt(3)
	v_add_f32_e32 v111, v111, v119
	s_waitcnt lgkmcnt(2)
	v_add_f32_e32 v112, v112, v120
	s_waitcnt lgkmcnt(1)
	v_add_f32_e32 v113, v113, v121
	s_waitcnt lgkmcnt(0)
	v_add_f32_e32 v114, v114, v122
	v_mov_b32_e32 v127, 0x358637bd
	s_mov_b32 s6, 0x3b800000
	v_fma_f32 v124, v107, s6, v127
	v_rsq_f32_e32 v124, v124
	s_nop 0
	v_mul_f32_e32 v0, v0, v124
	v_mul_f32_e32 v1, v1, v124
	v_mul_f32_e32 v2, v2, v124
	v_mul_f32_e32 v3, v3, v124
	v_fma_f32 v0, v0, v88, v92
	v_fma_f32 v1, v1, v89, v93
	v_fma_f32 v2, v2, v90, v94
	v_fma_f32 v3, v3, v91, v95
	v_mul_f32_e32 v125, 0xbfb8aa3b, v0
	v_mul_f32_e32 v126, 0xbfb8aa3b, v1
	v_mul_f32_e32 v115, 0xbfb8aa3b, v2
	v_mul_f32_e32 v116, 0xbfb8aa3b, v3
	v_exp_f32_e32 v125, v125
	v_exp_f32_e32 v126, v126
	v_exp_f32_e32 v115, v115
	v_exp_f32_e32 v116, v116
	s_nop 0
	v_add_f32_e32 v125, 1.0, v125
	v_add_f32_e32 v126, 1.0, v126
	v_add_f32_e32 v115, 1.0, v115
	v_add_f32_e32 v116, 1.0, v116
	v_rcp_f32_e32 v125, v125
	v_rcp_f32_e32 v126, v126
	v_rcp_f32_e32 v115, v115
	v_rcp_f32_e32 v116, v116
	s_nop 0
	v_mul_f32_e32 v0, v0, v125
	v_mul_f32_e32 v1, v1, v126
	v_mul_f32_e32 v2, v2, v115
	v_mul_f32_e32 v3, v3, v116
	v_cvt_pk_bf16_f32 v0, v0, v1
	v_cvt_pk_bf16_f32 v1, v2, v3
	v_mov_b32_e32 v117, v104
	global_store_dwordx2 v117, v[0:1], s[82:83]
	v_fma_f32 v124, v108, s6, v127
	v_rsq_f32_e32 v124, v124
	s_nop 0
	v_mul_f32_e32 v4, v4, v124
	v_mul_f32_e32 v5, v5, v124
	v_mul_f32_e32 v6, v6, v124
	v_mul_f32_e32 v7, v7, v124
	v_fma_f32 v4, v4, v88, v92
	v_fma_f32 v5, v5, v89, v93
	v_fma_f32 v6, v6, v90, v94
	v_fma_f32 v7, v7, v91, v95
	v_mul_f32_e32 v125, 0xbfb8aa3b, v4
	v_mul_f32_e32 v126, 0xbfb8aa3b, v5
	v_mul_f32_e32 v115, 0xbfb8aa3b, v6
	v_mul_f32_e32 v116, 0xbfb8aa3b, v7
	v_exp_f32_e32 v125, v125
	v_exp_f32_e32 v126, v126
	v_exp_f32_e32 v115, v115
	v_exp_f32_e32 v116, v116
	s_nop 0
	v_add_f32_e32 v125, 1.0, v125
	v_add_f32_e32 v126, 1.0, v126
	v_add_f32_e32 v115, 1.0, v115
	v_add_f32_e32 v116, 1.0, v116
	v_rcp_f32_e32 v125, v125
	v_rcp_f32_e32 v126, v126
	v_rcp_f32_e32 v115, v115
	v_rcp_f32_e32 v116, v116
	s_nop 0
	v_mul_f32_e32 v4, v4, v125
	v_mul_f32_e32 v5, v5, v126
	v_mul_f32_e32 v6, v6, v115
	v_mul_f32_e32 v7, v7, v116
	v_cvt_pk_bf16_f32 v4, v4, v5
	v_cvt_pk_bf16_f32 v5, v6, v7
	v_add_u32_e32 v117, 0x800, v104
	global_store_dwordx2 v117, v[4:5], s[82:83]
	v_fma_f32 v124, v109, s6, v127
	v_rsq_f32_e32 v124, v124
	s_nop 0
	v_mul_f32_e32 v8, v8, v124
	v_mul_f32_e32 v9, v9, v124
	v_mul_f32_e32 v10, v10, v124
	v_mul_f32_e32 v11, v11, v124
	v_fma_f32 v8, v8, v88, v92
	v_fma_f32 v9, v9, v89, v93
	v_fma_f32 v10, v10, v90, v94
	v_fma_f32 v11, v11, v91, v95
	v_mul_f32_e32 v125, 0xbfb8aa3b, v8
	v_mul_f32_e32 v126, 0xbfb8aa3b, v9
	v_mul_f32_e32 v115, 0xbfb8aa3b, v10
	v_mul_f32_e32 v116, 0xbfb8aa3b, v11
	v_exp_f32_e32 v125, v125
	v_exp_f32_e32 v126, v126
	v_exp_f32_e32 v115, v115
	v_exp_f32_e32 v116, v116
	s_nop 0
	v_add_f32_e32 v125, 1.0, v125
	v_add_f32_e32 v126, 1.0, v126
	v_add_f32_e32 v115, 1.0, v115
	v_add_f32_e32 v116, 1.0, v116
	v_rcp_f32_e32 v125, v125
	v_rcp_f32_e32 v126, v126
	v_rcp_f32_e32 v115, v115
	v_rcp_f32_e32 v116, v116
	s_nop 0
	v_mul_f32_e32 v8, v8, v125
	v_mul_f32_e32 v9, v9, v126
	v_mul_f32_e32 v10, v10, v115
	v_mul_f32_e32 v11, v11, v116
	v_cvt_pk_bf16_f32 v8, v8, v9
	v_cvt_pk_bf16_f32 v9, v10, v11
	v_add_u32_e32 v117, 0x1000, v104
	global_store_dwordx2 v117, v[8:9], s[82:83]
	v_fma_f32 v124, v110, s6, v127
	v_rsq_f32_e32 v124, v124
	s_nop 0
	v_mul_f32_e32 v12, v12, v124
	v_mul_f32_e32 v13, v13, v124
	v_mul_f32_e32 v14, v14, v124
	v_mul_f32_e32 v15, v15, v124
	v_fma_f32 v12, v12, v88, v92
	v_fma_f32 v13, v13, v89, v93
	v_fma_f32 v14, v14, v90, v94
	v_fma_f32 v15, v15, v91, v95
	v_mul_f32_e32 v125, 0xbfb8aa3b, v12
	v_mul_f32_e32 v126, 0xbfb8aa3b, v13
	v_mul_f32_e32 v115, 0xbfb8aa3b, v14
	v_mul_f32_e32 v116, 0xbfb8aa3b, v15
	v_exp_f32_e32 v125, v125
	v_exp_f32_e32 v126, v126
	v_exp_f32_e32 v115, v115
	v_exp_f32_e32 v116, v116
	s_nop 0
	v_add_f32_e32 v125, 1.0, v125
	v_add_f32_e32 v126, 1.0, v126
	v_add_f32_e32 v115, 1.0, v115
	v_add_f32_e32 v116, 1.0, v116
	v_rcp_f32_e32 v125, v125
	v_rcp_f32_e32 v126, v126
	v_rcp_f32_e32 v115, v115
	v_rcp_f32_e32 v116, v116
	s_nop 0
	v_mul_f32_e32 v12, v12, v125
	v_mul_f32_e32 v13, v13, v126
	v_mul_f32_e32 v14, v14, v115
	v_mul_f32_e32 v15, v15, v116
	v_cvt_pk_bf16_f32 v12, v12, v13
	v_cvt_pk_bf16_f32 v13, v14, v15
	v_add_u32_e32 v117, 0x1800, v104
	global_store_dwordx2 v117, v[12:13], s[82:83]
	v_fma_f32 v124, v111, s6, v127
	v_rsq_f32_e32 v124, v124
	s_nop 0
	v_mul_f32_e32 v16, v16, v124
	v_mul_f32_e32 v17, v17, v124
	v_mul_f32_e32 v18, v18, v124
	v_mul_f32_e32 v19, v19, v124
	v_fma_f32 v16, v16, v88, v92
	v_fma_f32 v17, v17, v89, v93
	v_fma_f32 v18, v18, v90, v94
	v_fma_f32 v19, v19, v91, v95
	v_mul_f32_e32 v125, 0xbfb8aa3b, v16
	v_mul_f32_e32 v126, 0xbfb8aa3b, v17
	v_mul_f32_e32 v115, 0xbfb8aa3b, v18
	v_mul_f32_e32 v116, 0xbfb8aa3b, v19
	v_exp_f32_e32 v125, v125
	v_exp_f32_e32 v126, v126
	v_exp_f32_e32 v115, v115
	v_exp_f32_e32 v116, v116
	s_nop 0
	v_add_f32_e32 v125, 1.0, v125
	v_add_f32_e32 v126, 1.0, v126
	v_add_f32_e32 v115, 1.0, v115
	v_add_f32_e32 v116, 1.0, v116
	v_rcp_f32_e32 v125, v125
	v_rcp_f32_e32 v126, v126
	v_rcp_f32_e32 v115, v115
	v_rcp_f32_e32 v116, v116
	s_nop 0
	v_mul_f32_e32 v16, v16, v125
	v_mul_f32_e32 v17, v17, v126
	v_mul_f32_e32 v18, v18, v115
	v_mul_f32_e32 v19, v19, v116
	v_cvt_pk_bf16_f32 v16, v16, v17
	v_cvt_pk_bf16_f32 v17, v18, v19
	v_add_u32_e32 v117, 0x2000, v104
	global_store_dwordx2 v117, v[16:17], s[82:83]
	v_fma_f32 v124, v112, s6, v127
	v_rsq_f32_e32 v124, v124
	s_nop 0
	v_mul_f32_e32 v20, v20, v124
	v_mul_f32_e32 v21, v21, v124
	v_mul_f32_e32 v22, v22, v124
	v_mul_f32_e32 v23, v23, v124
	v_fma_f32 v20, v20, v88, v92
	v_fma_f32 v21, v21, v89, v93
	v_fma_f32 v22, v22, v90, v94
	v_fma_f32 v23, v23, v91, v95
	v_mul_f32_e32 v125, 0xbfb8aa3b, v20
	v_mul_f32_e32 v126, 0xbfb8aa3b, v21
	v_mul_f32_e32 v115, 0xbfb8aa3b, v22
	v_mul_f32_e32 v116, 0xbfb8aa3b, v23
	v_exp_f32_e32 v125, v125
	v_exp_f32_e32 v126, v126
	v_exp_f32_e32 v115, v115
	v_exp_f32_e32 v116, v116
	s_nop 0
	v_add_f32_e32 v125, 1.0, v125
	v_add_f32_e32 v126, 1.0, v126
	v_add_f32_e32 v115, 1.0, v115
	v_add_f32_e32 v116, 1.0, v116
	v_rcp_f32_e32 v125, v125
	v_rcp_f32_e32 v126, v126
	v_rcp_f32_e32 v115, v115
	v_rcp_f32_e32 v116, v116
	s_nop 0
	v_mul_f32_e32 v20, v20, v125
	v_mul_f32_e32 v21, v21, v126
	v_mul_f32_e32 v22, v22, v115
	v_mul_f32_e32 v23, v23, v116
	v_cvt_pk_bf16_f32 v20, v20, v21
	v_cvt_pk_bf16_f32 v21, v22, v23
	v_add_u32_e32 v117, 0x2800, v104
	global_store_dwordx2 v117, v[20:21], s[82:83]
	v_fma_f32 v124, v113, s6, v127
	v_rsq_f32_e32 v124, v124
	s_nop 0
	v_mul_f32_e32 v24, v24, v124
	v_mul_f32_e32 v25, v25, v124
	v_mul_f32_e32 v26, v26, v124
	v_mul_f32_e32 v27, v27, v124
	v_fma_f32 v24, v24, v88, v92
	v_fma_f32 v25, v25, v89, v93
	v_fma_f32 v26, v26, v90, v94
	v_fma_f32 v27, v27, v91, v95
	v_mul_f32_e32 v125, 0xbfb8aa3b, v24
	v_mul_f32_e32 v126, 0xbfb8aa3b, v25
	v_mul_f32_e32 v115, 0xbfb8aa3b, v26
	v_mul_f32_e32 v116, 0xbfb8aa3b, v27
	v_exp_f32_e32 v125, v125
	v_exp_f32_e32 v126, v126
	v_exp_f32_e32 v115, v115
	v_exp_f32_e32 v116, v116
	s_nop 0
	v_add_f32_e32 v125, 1.0, v125
	v_add_f32_e32 v126, 1.0, v126
	v_add_f32_e32 v115, 1.0, v115
	v_add_f32_e32 v116, 1.0, v116
	v_rcp_f32_e32 v125, v125
	v_rcp_f32_e32 v126, v126
	v_rcp_f32_e32 v115, v115
	v_rcp_f32_e32 v116, v116
	s_nop 0
	v_mul_f32_e32 v24, v24, v125
	v_mul_f32_e32 v25, v25, v126
	v_mul_f32_e32 v26, v26, v115
	v_mul_f32_e32 v27, v27, v116
	v_cvt_pk_bf16_f32 v24, v24, v25
	v_cvt_pk_bf16_f32 v25, v26, v27
	v_add_u32_e32 v117, 0x3000, v104
	global_store_dwordx2 v117, v[24:25], s[82:83]
	v_fma_f32 v124, v114, s6, v127
	v_rsq_f32_e32 v124, v124
	s_nop 0
	v_mul_f32_e32 v28, v28, v124
	v_mul_f32_e32 v29, v29, v124
	v_mul_f32_e32 v30, v30, v124
	v_mul_f32_e32 v31, v31, v124
	v_fma_f32 v28, v28, v88, v92
	v_fma_f32 v29, v29, v89, v93
	v_fma_f32 v30, v30, v90, v94
	v_fma_f32 v31, v31, v91, v95
	v_mul_f32_e32 v125, 0xbfb8aa3b, v28
	v_mul_f32_e32 v126, 0xbfb8aa3b, v29
	v_mul_f32_e32 v115, 0xbfb8aa3b, v30
	v_mul_f32_e32 v116, 0xbfb8aa3b, v31
	v_exp_f32_e32 v125, v125
	v_exp_f32_e32 v126, v126
	v_exp_f32_e32 v115, v115
	v_exp_f32_e32 v116, v116
	s_nop 0
	v_add_f32_e32 v125, 1.0, v125
	v_add_f32_e32 v126, 1.0, v126
	v_add_f32_e32 v115, 1.0, v115
	v_add_f32_e32 v116, 1.0, v116
	v_rcp_f32_e32 v125, v125
	v_rcp_f32_e32 v126, v126
	v_rcp_f32_e32 v115, v115
	v_rcp_f32_e32 v116, v116
	s_nop 0
	v_mul_f32_e32 v28, v28, v125
	v_mul_f32_e32 v29, v29, v126
	v_mul_f32_e32 v30, v30, v115
	v_mul_f32_e32 v31, v31, v116
	v_cvt_pk_bf16_f32 v28, v28, v29
	v_cvt_pk_bf16_f32 v29, v30, v31
	v_add_u32_e32 v117, 0x3800, v104
	global_store_dwordx2 v117, v[28:29], s[82:83]
	s_add_i32 s16, s16, s44
	s_cmpk_lt_i32 s16, 0x1000
	s_cbranch_scc1 .Lcv_item
.Lcv_done:
.LBB0_362:
	s_cmp_lt_i32 s46, 0x8000
	s_cselect_b64 s[0:1], -1, 0
	s_cmpk_gt_i32 s46, 0x7fff
	v_lshrrev_b32_e32 v38, 4, v246
	s_cbranch_scc1 .LBB0_395
	s_ashr_i32 s47, s46, 31
	s_add_i32 s72, s46, -7
	s_lshl_b64 s[6:7], s[46:47], 11
	s_add_u32 s6, s48, s6
	v_lshlrev_b32_e32 v4, 3, v246
	v_mov_b32_e32 v5, v97
	s_addc_u32 s7, s49, s7
	v_lshl_add_u64 v[2:3], s[6:7], 0, v[4:5]
	s_mov_b64 s[6:7], 0x8600400
	s_ashr_i32 s45, s44, 31
	v_lshl_add_u64 v[2:3], v[2:3], 0, s[6:7]
	s_lshl_b64 s[74:75], s[44:45], 11
	s_lshl_b64 s[6:7], s[46:47], 9
	s_add_u32 s6, s68, s6
	v_mov_b32_e32 v107, v97
	s_addc_u32 s7, s69, s7
	v_lshlrev_b32_e64 v39, v38, 2
	v_lshl_add_u64 v[0:1], s[68:69], 0, v[106:107]
	v_lshl_add_u64 v[4:5], s[6:7], 0, v[4:5]
	s_lshl_b64 s[76:77], s[44:45], 9
	s_branch .LBB0_365
